# GEMM loops (P1,P3,P5,P7,P8): first K iteration peeled with MFMA C operand 0; the 128 v_mov accumulator zero-inits per tile and wave removed
# speedup vs baseline: 1.0074x; 1.0074x over previous
.LBB0_57:
	s_add_u32 s20, s44, 0x100
	s_addc_u32 s21, s45, 0
	s_mov_b32 s22, -2
	v_add_u32_e32 v194, 0x10000, v143
	s_add_u32 s44, s42, 0x100
	s_addc_u32 s45, s43, 0
	s_add_i32 s23, 0, 0x10000
	ds_read_b128 v[146:149], v194
	ds_read_b128 v[150:153], v194 offset:1024
	ds_read_b128 v[154:157], v194 offset:2048
	ds_read_b128 v[158:161], v194 offset:3072
	s_cmp_eq_u32 s22, 40
	s_cselect_b32 s49, s1, s45
	s_cselect_b32 s48, s0, s44
	s_cselect_b32 s47, s41, s21
	s_cselect_b32 s46, s40, s20
	s_add_i32 m0, s52, 0xc000
	ds_read_b128 v[162:165], v144
	ds_read_b128 v[166:169], v144 offset:1024
	ds_read_b128 v[170:173], v144 offset:2048
	ds_read_b128 v[174:177], v144 offset:3072
	ds_read_b128 v[178:181], v144 offset:4096
	ds_read_b128 v[182:185], v144 offset:5120
	ds_read_b128 v[186:189], v144 offset:6144
	global_load_lds_dwordx4 v138, s[42:43]
	s_add_i32 m0, s52, 0xe000
	ds_read_b128 v[190:193], v144 offset:7168
	global_load_lds_dwordx4 v140, s[42:43]
	s_waitcnt lgkmcnt(8)
	s_barrier
	s_waitcnt lgkmcnt(0)
	v_mfma_f32_16x16x32_bf16 v[128:131], v[146:149], v[162:165], 0
	v_mfma_f32_16x16x32_bf16 v[124:127], v[154:157], v[162:165], 0
	v_mfma_f32_16x16x32_bf16 v[120:123], v[146:149], v[170:173], 0
	v_mfma_f32_16x16x32_bf16 v[116:119], v[154:157], v[170:173], 0
	v_mfma_f32_16x16x32_bf16 v[104:107], v[146:149], v[178:181], 0
	v_mfma_f32_16x16x32_bf16 v[100:103], v[154:157], v[178:181], 0
	v_mfma_f32_16x16x32_bf16 v[88:91], v[146:149], v[186:189], 0
	v_mfma_f32_16x16x32_bf16 v[84:87], v[154:157], v[186:189], 0
	v_mfma_f32_16x16x32_bf16 v[128:131], v[150:153], v[166:169], v[128:131]
	v_mfma_f32_16x16x32_bf16 v[124:127], v[158:161], v[166:169], v[124:127]
	v_mfma_f32_16x16x32_bf16 v[120:123], v[150:153], v[174:177], v[120:123]
	v_mfma_f32_16x16x32_bf16 v[116:119], v[158:161], v[174:177], v[116:119]
	v_mfma_f32_16x16x32_bf16 v[104:107], v[150:153], v[182:185], v[104:107]
	v_mfma_f32_16x16x32_bf16 v[100:103], v[158:161], v[182:185], v[100:103]
	v_mfma_f32_16x16x32_bf16 v[88:91], v[150:153], v[190:193], v[88:91]
	v_mfma_f32_16x16x32_bf16 v[84:87], v[158:161], v[190:193], v[84:87]
	s_barrier
	s_add_i32 s26, 0, 0x14000
	s_add_i32 s23, s23, s37
	s_mov_b32 m0, s23
	ds_read_b128 v[202:205], v194 offset:16384
	ds_read_b128 v[206:209], v194 offset:17408
	ds_read_b128 v[210:213], v194 offset:18432
	global_load_lds_dwordx4 v132, s[46:47]
	s_add_i32 m0, s23, 0x2000
	ds_read_b128 v[214:217], v194 offset:19456
	global_load_lds_dwordx4 v136, s[46:47]
	s_barrier
	s_waitcnt lgkmcnt(0)
	v_mfma_f32_16x16x32_bf16 v[112:115], v[202:205], v[162:165], 0
	v_mfma_f32_16x16x32_bf16 v[108:111], v[210:213], v[162:165], 0
	v_mfma_f32_16x16x32_bf16 v[96:99], v[202:205], v[170:173], 0
	v_mfma_f32_16x16x32_bf16 v[92:95], v[210:213], v[170:173], 0
	v_mfma_f32_16x16x32_bf16 v[80:83], v[202:205], v[178:181], 0
	v_mfma_f32_16x16x32_bf16 v[76:79], v[210:213], v[178:181], 0
	v_mfma_f32_16x16x32_bf16 v[72:75], v[202:205], v[186:189], 0
	v_mfma_f32_16x16x32_bf16 v[68:71], v[210:213], v[186:189], 0
	v_mfma_f32_16x16x32_bf16 v[112:115], v[206:209], v[166:169], v[112:115]
	v_mfma_f32_16x16x32_bf16 v[108:111], v[214:217], v[166:169], v[108:111]
	v_mfma_f32_16x16x32_bf16 v[96:99], v[206:209], v[174:177], v[96:99]
	v_mfma_f32_16x16x32_bf16 v[92:95], v[214:217], v[174:177], v[92:95]
	v_mfma_f32_16x16x32_bf16 v[80:83], v[206:209], v[182:185], v[80:83]
	v_mfma_f32_16x16x32_bf16 v[76:79], v[214:217], v[182:185], v[76:79]
	v_mfma_f32_16x16x32_bf16 v[72:75], v[206:209], v[190:193], v[72:75]
	v_mfma_f32_16x16x32_bf16 v[68:71], v[214:217], v[190:193], v[68:71]
	s_mov_b32 m0, s52
	s_barrier
	ds_read_b128 v[162:165], v144 offset:16384
	ds_read_b128 v[166:169], v144 offset:17408
	ds_read_b128 v[170:173], v144 offset:18432
	ds_read_b128 v[174:177], v144 offset:19456
	ds_read_b128 v[178:181], v144 offset:20480
	ds_read_b128 v[182:185], v144 offset:21504
	ds_read_b128 v[186:189], v144 offset:22528
	global_load_lds_dwordx4 v0, s[48:49]
	s_mov_b32 m0, s53
	ds_read_b128 v[190:193], v144 offset:23552
	global_load_lds_dwordx4 v134, s[48:49]
	s_barrier
	s_waitcnt lgkmcnt(0)
	v_mfma_f32_16x16x32_bf16 v[64:67], v[146:149], v[162:165], 0
	v_mfma_f32_16x16x32_bf16 v[60:63], v[154:157], v[162:165], 0
	v_mfma_f32_16x16x32_bf16 v[56:59], v[146:149], v[170:173], 0
	v_mfma_f32_16x16x32_bf16 v[52:55], v[154:157], v[170:173], 0
	v_mfma_f32_16x16x32_bf16 v[40:43], v[146:149], v[178:181], 0
	v_mfma_f32_16x16x32_bf16 v[36:39], v[154:157], v[178:181], 0
	v_mfma_f32_16x16x32_bf16 v[24:27], v[146:149], v[186:189], 0
	v_mfma_f32_16x16x32_bf16 v[16:19], v[154:157], v[186:189], 0
	v_mfma_f32_16x16x32_bf16 v[64:67], v[150:153], v[166:169], v[64:67]
	v_mfma_f32_16x16x32_bf16 v[60:63], v[158:161], v[166:169], v[60:63]
	v_mfma_f32_16x16x32_bf16 v[56:59], v[150:153], v[174:177], v[56:59]
	v_mfma_f32_16x16x32_bf16 v[52:55], v[158:161], v[174:177], v[52:55]
	v_mfma_f32_16x16x32_bf16 v[40:43], v[150:153], v[182:185], v[40:43]
	v_mfma_f32_16x16x32_bf16 v[36:39], v[158:161], v[182:185], v[36:39]
	v_mfma_f32_16x16x32_bf16 v[24:27], v[150:153], v[190:193], v[24:27]
	v_mfma_f32_16x16x32_bf16 v[16:19], v[158:161], v[190:193], v[16:19]
	s_barrier
	s_add_i32 s23, s26, s37
	s_mov_b32 m0, s23
	s_add_u32 s24, s46, 0xb0000
	s_addc_u32 s25, s47, 0
	global_load_lds_dwordx4 v132, s[24:25]
	s_add_i32 m0, s23, 0x2000
	s_waitcnt vmcnt(5)
	global_load_lds_dwordx4 v136, s[24:25]
	s_barrier
	v_mfma_f32_16x16x32_bf16 v[48:51], v[202:205], v[162:165], 0
	v_mfma_f32_16x16x32_bf16 v[44:47], v[210:213], v[162:165], 0
	v_mfma_f32_16x16x32_bf16 v[32:35], v[202:205], v[170:173], 0
	v_mfma_f32_16x16x32_bf16 v[28:31], v[210:213], v[170:173], 0
	v_mfma_f32_16x16x32_bf16 v[20:23], v[202:205], v[178:181], 0
	v_mfma_f32_16x16x32_bf16 v[12:15], v[210:213], v[178:181], 0
	v_mfma_f32_16x16x32_bf16 v[8:11], v[202:205], v[186:189], 0
	v_mfma_f32_16x16x32_bf16 v[4:7], v[210:213], v[186:189], 0
	v_mfma_f32_16x16x32_bf16 v[48:51], v[206:209], v[166:169], v[48:51]
	v_mfma_f32_16x16x32_bf16 v[44:47], v[214:217], v[166:169], v[44:47]
	v_mfma_f32_16x16x32_bf16 v[32:35], v[206:209], v[174:177], v[32:35]
	v_mfma_f32_16x16x32_bf16 v[28:31], v[214:217], v[174:177], v[28:31]
	v_mfma_f32_16x16x32_bf16 v[20:23], v[206:209], v[182:185], v[20:23]
	v_mfma_f32_16x16x32_bf16 v[12:15], v[214:217], v[182:185], v[12:15]
	v_mfma_f32_16x16x32_bf16 v[8:11], v[206:209], v[190:193], v[8:11]
	v_mfma_f32_16x16x32_bf16 v[4:7], v[214:217], v[190:193], v[4:7]
	s_add_i32 s23, 0, 0x18000
	s_barrier
	ds_read_b128 v[146:149], v194 offset:32768
	ds_read_b128 v[150:153], v194 offset:33792
	ds_read_b128 v[154:157], v194 offset:34816
	ds_read_b128 v[158:161], v194 offset:35840
	s_add_u32 s24, s48, 0xb0000
	s_addc_u32 s25, s49, 0
	s_mov_b32 m0, s54
	ds_read_b128 v[162:165], v144 offset:32768
	ds_read_b128 v[166:169], v144 offset:33792
	ds_read_b128 v[170:173], v144 offset:34816
	ds_read_b128 v[174:177], v144 offset:35840
	ds_read_b128 v[178:181], v144 offset:36864
	ds_read_b128 v[182:185], v144 offset:37888
	ds_read_b128 v[186:189], v144 offset:38912
	global_load_lds_dwordx4 v0, s[24:25]
	s_mov_b32 m0, s55
	ds_read_b128 v[190:193], v144 offset:39936
	global_load_lds_dwordx4 v134, s[24:25]
	s_waitcnt lgkmcnt(8)
	s_barrier
	s_waitcnt lgkmcnt(0)
	v_mfma_f32_16x16x32_bf16 v[128:131], v[146:149], v[162:165], v[128:131]
	v_mfma_f32_16x16x32_bf16 v[124:127], v[154:157], v[162:165], v[124:127]
	v_mfma_f32_16x16x32_bf16 v[120:123], v[146:149], v[170:173], v[120:123]
	v_mfma_f32_16x16x32_bf16 v[116:119], v[154:157], v[170:173], v[116:119]
	v_mfma_f32_16x16x32_bf16 v[104:107], v[146:149], v[178:181], v[104:107]
	v_mfma_f32_16x16x32_bf16 v[100:103], v[154:157], v[178:181], v[100:103]
	v_mfma_f32_16x16x32_bf16 v[88:91], v[146:149], v[186:189], v[88:91]
	v_mfma_f32_16x16x32_bf16 v[84:87], v[154:157], v[186:189], v[84:87]
	v_mfma_f32_16x16x32_bf16 v[128:131], v[150:153], v[166:169], v[128:131]
	v_mfma_f32_16x16x32_bf16 v[124:127], v[158:161], v[166:169], v[124:127]
	v_mfma_f32_16x16x32_bf16 v[120:123], v[150:153], v[174:177], v[120:123]
	v_mfma_f32_16x16x32_bf16 v[116:119], v[158:161], v[174:177], v[116:119]
	v_mfma_f32_16x16x32_bf16 v[104:107], v[150:153], v[182:185], v[104:107]
	v_mfma_f32_16x16x32_bf16 v[100:103], v[158:161], v[182:185], v[100:103]
	v_mfma_f32_16x16x32_bf16 v[88:91], v[150:153], v[190:193], v[88:91]
	v_mfma_f32_16x16x32_bf16 v[84:87], v[158:161], v[190:193], v[84:87]
	s_barrier
	s_add_i32 s26, 0, 0x1c000
	s_add_i32 s23, s23, s37
	s_mov_b32 m0, s23
	ds_read_b128 v[202:205], v194 offset:49152
	ds_read_b128 v[206:209], v194 offset:50176
	ds_read_b128 v[210:213], v194 offset:51200
	s_add_u32 s98, s46, 0x80
	s_addc_u32 s99, s47, 0
	global_load_lds_dwordx4 v132, s[98:99]
	s_add_i32 m0, s23, 0x2000
	ds_read_b128 v[214:217], v194 offset:52224
	global_load_lds_dwordx4 v136, s[98:99]
	s_barrier
	s_waitcnt lgkmcnt(0)
	v_mfma_f32_16x16x32_bf16 v[112:115], v[202:205], v[162:165], v[112:115]
	v_mfma_f32_16x16x32_bf16 v[108:111], v[210:213], v[162:165], v[108:111]
	v_mfma_f32_16x16x32_bf16 v[96:99], v[202:205], v[170:173], v[96:99]
	v_mfma_f32_16x16x32_bf16 v[92:95], v[210:213], v[170:173], v[92:95]
	v_mfma_f32_16x16x32_bf16 v[80:83], v[202:205], v[178:181], v[80:83]
	v_mfma_f32_16x16x32_bf16 v[76:79], v[210:213], v[178:181], v[76:79]
	v_mfma_f32_16x16x32_bf16 v[72:75], v[202:205], v[186:189], v[72:75]
	v_mfma_f32_16x16x32_bf16 v[68:71], v[210:213], v[186:189], v[68:71]
	v_mfma_f32_16x16x32_bf16 v[112:115], v[206:209], v[166:169], v[112:115]
	v_mfma_f32_16x16x32_bf16 v[108:111], v[214:217], v[166:169], v[108:111]
	v_mfma_f32_16x16x32_bf16 v[96:99], v[206:209], v[174:177], v[96:99]
	v_mfma_f32_16x16x32_bf16 v[92:95], v[214:217], v[174:177], v[92:95]
	v_mfma_f32_16x16x32_bf16 v[80:83], v[206:209], v[182:185], v[80:83]
	v_mfma_f32_16x16x32_bf16 v[76:79], v[214:217], v[182:185], v[76:79]
	v_mfma_f32_16x16x32_bf16 v[72:75], v[206:209], v[190:193], v[72:75]
	v_mfma_f32_16x16x32_bf16 v[68:71], v[214:217], v[190:193], v[68:71]
	s_mov_b32 m0, s56
	s_barrier
	ds_read_b128 v[162:165], v144 offset:49152
	ds_read_b128 v[166:169], v144 offset:50176
	ds_read_b128 v[170:173], v144 offset:51200
	ds_read_b128 v[174:177], v144 offset:52224
	ds_read_b128 v[178:181], v144 offset:53248
	ds_read_b128 v[182:185], v144 offset:54272
	ds_read_b128 v[186:189], v144 offset:55296
	s_add_u32 s98, s48, 0x80
	s_addc_u32 s99, s49, 0
	global_load_lds_dwordx4 v0, s[98:99]
	s_mov_b32 m0, s57
	ds_read_b128 v[190:193], v144 offset:56320
	global_load_lds_dwordx4 v134, s[98:99]
	s_barrier
	s_waitcnt lgkmcnt(0)
	v_mfma_f32_16x16x32_bf16 v[64:67], v[146:149], v[162:165], v[64:67]
	v_mfma_f32_16x16x32_bf16 v[60:63], v[154:157], v[162:165], v[60:63]
	v_mfma_f32_16x16x32_bf16 v[56:59], v[146:149], v[170:173], v[56:59]
	v_mfma_f32_16x16x32_bf16 v[52:55], v[154:157], v[170:173], v[52:55]
	v_mfma_f32_16x16x32_bf16 v[40:43], v[146:149], v[178:181], v[40:43]
	v_mfma_f32_16x16x32_bf16 v[36:39], v[154:157], v[178:181], v[36:39]
	v_mfma_f32_16x16x32_bf16 v[24:27], v[146:149], v[186:189], v[24:27]
	v_mfma_f32_16x16x32_bf16 v[16:19], v[154:157], v[186:189], v[16:19]
	v_mfma_f32_16x16x32_bf16 v[64:67], v[150:153], v[166:169], v[64:67]
	v_mfma_f32_16x16x32_bf16 v[60:63], v[158:161], v[166:169], v[60:63]
	v_mfma_f32_16x16x32_bf16 v[56:59], v[150:153], v[174:177], v[56:59]
	v_mfma_f32_16x16x32_bf16 v[52:55], v[158:161], v[174:177], v[52:55]
	v_mfma_f32_16x16x32_bf16 v[40:43], v[150:153], v[182:185], v[40:43]
	v_mfma_f32_16x16x32_bf16 v[36:39], v[158:161], v[182:185], v[36:39]
	v_mfma_f32_16x16x32_bf16 v[24:27], v[150:153], v[190:193], v[24:27]
	v_mfma_f32_16x16x32_bf16 v[16:19], v[158:161], v[190:193], v[16:19]
	s_barrier
	s_add_i32 s23, s26, s37
	s_mov_b32 m0, s23
	s_add_u32 s24, s46, 0xb0080
	s_addc_u32 s25, s47, 0
	global_load_lds_dwordx4 v132, s[24:25]
	s_add_i32 m0, s23, 0x2000
	s_waitcnt vmcnt(5)
	global_load_lds_dwordx4 v136, s[24:25]
	s_barrier
	v_mfma_f32_16x16x32_bf16 v[48:51], v[202:205], v[162:165], v[48:51]
	v_mfma_f32_16x16x32_bf16 v[44:47], v[210:213], v[162:165], v[44:47]
	v_mfma_f32_16x16x32_bf16 v[32:35], v[202:205], v[170:173], v[32:35]
	v_mfma_f32_16x16x32_bf16 v[28:31], v[210:213], v[170:173], v[28:31]
	v_mfma_f32_16x16x32_bf16 v[20:23], v[202:205], v[178:181], v[20:23]
	v_mfma_f32_16x16x32_bf16 v[12:15], v[210:213], v[178:181], v[12:15]
	v_mfma_f32_16x16x32_bf16 v[8:11], v[202:205], v[186:189], v[8:11]
	v_mfma_f32_16x16x32_bf16 v[4:7], v[210:213], v[186:189], v[4:7]
	v_mfma_f32_16x16x32_bf16 v[48:51], v[206:209], v[166:169], v[48:51]
	v_mfma_f32_16x16x32_bf16 v[44:47], v[214:217], v[166:169], v[44:47]
	v_mfma_f32_16x16x32_bf16 v[32:35], v[206:209], v[174:177], v[32:35]
	v_mfma_f32_16x16x32_bf16 v[28:31], v[214:217], v[174:177], v[28:31]
	v_mfma_f32_16x16x32_bf16 v[20:23], v[206:209], v[182:185], v[20:23]
	v_mfma_f32_16x16x32_bf16 v[12:15], v[214:217], v[182:185], v[12:15]
	v_mfma_f32_16x16x32_bf16 v[8:11], v[206:209], v[190:193], v[8:11]
	v_mfma_f32_16x16x32_bf16 v[4:7], v[214:217], v[190:193], v[4:7]
	s_add_i32 s22, s22, 2
	s_add_u32 s20, s20, 0x100
	s_addc_u32 s21, s21, 0
	s_cmp_gt_u32 s22, 41
	s_mov_b64 s[42:43], s[44:45]
	s_barrier
	s_cbranch_scc1 .Lpeel_out_58

.Lpeel_out_58:
	v_lshl_add_u32 v146, s61, 8, v142
	v_cvt_pk_bf16_f32 v72, v72, v73
	v_cvt_pk_bf16_f32 v73, v74, v75
	v_cvt_pk_bf16_f32 v74, v68, v69
	v_add_u32_e32 v68, 0x80, v146
	s_lshl_b32 s20, s62, 8
	v_ashrrev_i32_e32 v147, 31, v146
	v_readlane_b32 s22, v252, 10
	v_cvt_pk_bf16_f32 v112, v112, v113
	v_cvt_pk_bf16_f32 v113, v114, v115
	v_cvt_pk_bf16_f32 v114, v108, v109
	v_or_b32_e32 v108, 16, v146
	v_ashrrev_i32_e32 v69, 31, v68
	v_cvt_pk_bf16_f32 v48, v48, v49
	v_cvt_pk_bf16_f32 v49, v50, v51
	v_cvt_pk_bf16_f32 v50, v44, v45
	v_add_u32_e32 v44, 0x90, v146
	s_ashr_i32 s21, s20, 31
	v_lshlrev_b64 v[148:149], 11, v[146:147]
	v_readlane_b32 s23, v252, 11
	v_ashrrev_i32_e32 v109, 31, v108
	v_cvt_pk_bf16_f32 v96, v96, v97
	v_cvt_pk_bf16_f32 v97, v98, v99
	v_cvt_pk_bf16_f32 v98, v92, v93
	v_or_b32_e32 v92, 32, v146
	v_lshlrev_b64 v[68:69], 11, v[68:69]
	v_ashrrev_i32_e32 v45, 31, v44
	v_cvt_pk_bf16_f32 v32, v32, v33
	v_cvt_pk_bf16_f32 v33, v34, v35
	v_cvt_pk_bf16_f32 v34, v28, v29
	v_add_u32_e32 v28, 0xa0, v146
	v_lshl_add_u64 v[148:149], s[22:23], 0, v[148:149]
	s_lshl_b64 s[42:43], s[20:21], 1
	v_lshlrev_b64 v[108:109], 11, v[108:109]
	v_ashrrev_i32_e32 v93, 31, v92
	v_cvt_pk_bf16_f32 v80, v80, v81
	v_cvt_pk_bf16_f32 v81, v82, v83
	v_cvt_pk_bf16_f32 v82, v76, v77
	v_or_b32_e32 v76, 48, v146
	v_lshl_add_u64 v[68:69], s[22:23], 0, v[68:69]
	v_lshlrev_b64 v[44:45], 11, v[44:45]
	v_ashrrev_i32_e32 v29, 31, v28
	v_cvt_pk_bf16_f32 v20, v20, v21
	v_cvt_pk_bf16_f32 v21, v22, v23
	v_cvt_pk_bf16_f32 v22, v12, v13
	v_add_u32_e32 v12, 0xb0, v146
	v_lshl_add_u64 v[148:149], v[148:149], 0, s[42:43]
	v_lshl_add_u64 v[108:109], s[22:23], 0, v[108:109]
	v_lshlrev_b64 v[92:93], 11, v[92:93]
	v_ashrrev_i32_e32 v77, 31, v76
	v_lshl_add_u64 v[68:69], v[68:69], 0, s[42:43]
	v_lshl_add_u64 v[44:45], s[22:23], 0, v[44:45]
	v_lshlrev_b64 v[28:29], 11, v[28:29]
	v_ashrrev_i32_e32 v13, 31, v12
	v_lshl_add_u64 v[148:149], v[148:149], 0, s[72:73]
	v_lshl_add_u64 v[108:109], v[108:109], 0, s[42:43]
	v_lshl_add_u64 v[92:93], s[22:23], 0, v[92:93]
	v_lshlrev_b64 v[76:77], 11, v[76:77]
	v_lshl_add_u64 v[68:69], v[68:69], 0, s[72:73]
	v_lshl_add_u64 v[44:45], v[44:45], 0, s[42:43]
	v_lshl_add_u64 v[28:29], s[22:23], 0, v[28:29]
	v_lshlrev_b64 v[12:13], 11, v[12:13]
	v_lshl_add_u64 v[148:149], v[148:149], 0, v[2:3]
	v_cvt_pk_bf16_f32 v115, v110, v111
	v_lshl_add_u64 v[108:109], v[108:109], 0, s[72:73]
	v_lshl_add_u64 v[92:93], v[92:93], 0, s[42:43]
	v_lshl_add_u64 v[76:77], s[22:23], 0, v[76:77]
	v_lshl_add_u64 v[68:69], v[68:69], 0, v[2:3]
	v_cvt_pk_bf16_f32 v51, v46, v47
	v_lshl_add_u64 v[44:45], v[44:45], 0, s[72:73]
	v_lshl_add_u64 v[28:29], v[28:29], 0, s[42:43]
	v_lshl_add_u64 v[12:13], s[22:23], 0, v[12:13]
	global_store_dwordx4 v[148:149], v[112:115], off offset:256
	v_cvt_pk_bf16_f32 v99, v94, v95
	v_lshl_add_u64 v[92:93], v[92:93], 0, s[72:73]
	v_lshl_add_u64 v[112:113], v[108:109], 0, v[2:3]
	v_lshl_add_u64 v[76:77], v[76:77], 0, s[42:43]
	global_store_dwordx4 v[68:69], v[48:51], off offset:256
	v_cvt_pk_bf16_f32 v35, v30, v31
	v_lshl_add_u64 v[28:29], v[28:29], 0, s[72:73]
	v_lshl_add_u64 v[48:49], v[44:45], 0, v[2:3]
	v_lshl_add_u64 v[12:13], v[12:13], 0, s[42:43]
	global_store_dwordx4 v[112:113], v[96:99], off offset:256
	v_cvt_pk_bf16_f32 v83, v78, v79
	v_lshl_add_u64 v[76:77], v[76:77], 0, s[72:73]
	v_lshl_add_u64 v[96:97], v[92:93], 0, v[2:3]
	global_store_dwordx4 v[48:49], v[32:35], off offset:256
	v_cvt_pk_bf16_f32 v23, v14, v15
	v_lshl_add_u64 v[12:13], v[12:13], 0, s[72:73]
	v_lshl_add_u64 v[32:33], v[28:29], 0, v[2:3]
	v_cvt_pk_bf16_f32 v128, v128, v129
	v_cvt_pk_bf16_f32 v129, v130, v131
	v_cvt_pk_bf16_f32 v130, v124, v125
	v_cvt_pk_bf16_f32 v131, v126, v127
	v_cvt_pk_bf16_f32 v108, v120, v121
	v_cvt_pk_bf16_f32 v109, v122, v123
	v_cvt_pk_bf16_f32 v110, v116, v117
	v_cvt_pk_bf16_f32 v111, v118, v119
	v_cvt_pk_bf16_f32 v92, v104, v105
	v_cvt_pk_bf16_f32 v93, v106, v107
	v_cvt_pk_bf16_f32 v94, v100, v101
	v_cvt_pk_bf16_f32 v95, v102, v103
	global_store_dwordx4 v[96:97], v[80:83], off offset:256
	v_cvt_pk_bf16_f32 v78, v84, v85
	v_cvt_pk_bf16_f32 v79, v86, v87
	v_lshl_add_u64 v[80:81], v[76:77], 0, v[2:3]
	v_cvt_pk_bf16_f32 v76, v88, v89
	v_cvt_pk_bf16_f32 v77, v90, v91
	v_cvt_pk_bf16_f32 v75, v70, v71
	v_cvt_pk_bf16_f32 v64, v64, v65
	v_cvt_pk_bf16_f32 v65, v66, v67
	v_cvt_pk_bf16_f32 v66, v60, v61
	v_cvt_pk_bf16_f32 v67, v62, v63
	v_cvt_pk_bf16_f32 v44, v56, v57
	v_cvt_pk_bf16_f32 v45, v58, v59
	v_cvt_pk_bf16_f32 v46, v52, v53
	v_cvt_pk_bf16_f32 v47, v54, v55
	v_cvt_pk_bf16_f32 v28, v40, v41
	v_cvt_pk_bf16_f32 v29, v42, v43
	v_cvt_pk_bf16_f32 v30, v36, v37
	v_cvt_pk_bf16_f32 v31, v38, v39
	global_store_dwordx4 v[32:33], v[20:23], off offset:256
	v_cvt_pk_bf16_f32 v14, v16, v17
	v_cvt_pk_bf16_f32 v15, v18, v19
	v_lshl_add_u64 v[20:21], v[12:13], 0, v[2:3]
	v_cvt_pk_bf16_f32 v12, v24, v25
	v_cvt_pk_bf16_f32 v13, v26, v27
	v_cvt_pk_bf16_f32 v8, v8, v9
	v_cvt_pk_bf16_f32 v9, v10, v11
	v_cvt_pk_bf16_f32 v10, v4, v5
	v_cvt_pk_bf16_f32 v11, v6, v7
	s_and_b64 vcc, exec, s[38:39]
	s_mov_b32 s62, s59
	s_mov_b32 s61, s60
	s_mov_b64 s[44:45], s[40:41]
	s_mov_b64 s[42:43], s[0:1]
	global_store_dwordx4 v[148:149], v[128:131], off
	global_store_dwordx4 v[112:113], v[108:111], off
	global_store_dwordx4 v[96:97], v[92:95], off
	global_store_dwordx4 v[80:81], v[76:79], off
	global_store_dwordx4 v[80:81], v[72:75], off offset:256
	global_store_dwordx4 v[68:69], v[64:67], off
	global_store_dwordx4 v[48:49], v[44:47], off
	global_store_dwordx4 v[32:33], v[28:31], off
	global_store_dwordx4 v[20:21], v[12:15], off
	global_store_dwordx4 v[20:21], v[8:11], off offset:256
	s_cbranch_vccz .LBB0_51
	s_waitcnt vmcnt(0)
	s_cmpk_gt_u32 s36, 0xff
	s_cbranch_scc1 .LBB0_62
	s_barrier

.LBB0_79:
	s_add_u32 s52, s52, 0x40080
	s_addc_u32 s53, s53, 0
	s_add_u32 s1, s54, 0x100
	s_addc_u32 s20, s55, 0
	s_mov_b32 s21, -2
	v_add_u32_e32 v198, 0x10000, v235
	s_add_u32 s22, s52, 0xfffc0080
	s_addc_u32 s23, s53, -1
	s_add_i32 s24, 0, 0x10000
	ds_read_b128 v[52:55], v198
	ds_read_b128 v[56:59], v198 offset:1024
	ds_read_b128 v[60:63], v198 offset:2048
	ds_read_b128 v[64:67], v198 offset:3072
	s_cmp_eq_u32 s21, 12
	s_cselect_b32 s57, s47, s23
	s_cselect_b32 s56, s46, s22
	s_cselect_b32 s55, s49, s20
	s_cselect_b32 s54, s48, s1
	s_add_i32 m0, s62, 0xc000
	ds_read_b128 v[76:79], v239
	ds_read_b128 v[80:83], v239 offset:1024
	ds_read_b128 v[84:87], v239 offset:2048
	ds_read_b128 v[88:91], v239 offset:3072
	ds_read_b128 v[92:95], v239 offset:4096
	ds_read_b128 v[96:99], v239 offset:5120
	ds_read_b128 v[100:103], v239 offset:6144
	global_load_lds_dwordx4 v206, s[52:53]
	s_add_i32 m0, s62, 0xe000
	ds_read_b128 v[104:107], v239 offset:7168
	global_load_lds_dwordx4 v208, s[52:53]
	s_waitcnt lgkmcnt(8)
	s_barrier
	s_waitcnt lgkmcnt(0)
	v_mfma_f32_16x16x32_bf16 v[160:163], v[52:55], v[92:95], 0
	v_mfma_f32_16x16x32_bf16 v[152:155], v[60:63], v[92:95], 0
	v_mfma_f32_16x16x32_bf16 v[144:147], v[52:55], v[100:103], 0
	v_mfma_f32_16x16x32_bf16 v[140:143], v[60:63], v[100:103], 0
	v_mfma_f32_16x16x32_bf16 v[116:119], v[52:55], v[76:79], 0
	v_mfma_f32_16x16x32_bf16 v[120:123], v[60:63], v[76:79], 0
	v_mfma_f32_16x16x32_bf16 v[124:127], v[52:55], v[84:87], 0
	v_mfma_f32_16x16x32_bf16 v[128:131], v[60:63], v[84:87], 0
	v_mfma_f32_16x16x32_bf16 v[160:163], v[56:59], v[96:99], v[160:163]
	v_mfma_f32_16x16x32_bf16 v[152:155], v[64:67], v[96:99], v[152:155]
	v_mfma_f32_16x16x32_bf16 v[144:147], v[56:59], v[104:107], v[144:147]
	v_mfma_f32_16x16x32_bf16 v[140:143], v[64:67], v[104:107], v[140:143]
	v_mfma_f32_16x16x32_bf16 v[116:119], v[56:59], v[80:83], v[116:119]
	v_mfma_f32_16x16x32_bf16 v[120:123], v[64:67], v[80:83], v[120:123]
	v_mfma_f32_16x16x32_bf16 v[124:127], v[56:59], v[88:91], v[124:127]
	v_mfma_f32_16x16x32_bf16 v[128:131], v[64:67], v[88:91], v[128:131]
	s_barrier
	s_add_i32 s25, 0, 0x14000
	s_add_i32 s22, s24, s60
	s_mov_b32 m0, s22
	ds_read_b128 v[168:171], v198 offset:16384
	ds_read_b128 v[176:179], v198 offset:17408
	ds_read_b128 v[184:187], v198 offset:18432
	global_load_lds_dwordx4 v2, s[54:55]
	s_add_i32 m0, s22, 0x2000
	ds_read_b128 v[192:195], v198 offset:19456
	global_load_lds_dwordx4 v0, s[54:55]
	s_barrier
	s_waitcnt lgkmcnt(0)
	v_mfma_f32_16x16x32_bf16 v[188:191], v[168:171], v[76:79], 0
	v_mfma_f32_16x16x32_bf16 v[76:79], v[184:187], v[76:79], 0
	v_mfma_f32_16x16x32_bf16 v[188:191], v[176:179], v[80:83], v[188:191]
	v_mfma_f32_16x16x32_bf16 v[76:79], v[192:195], v[80:83], v[76:79]
	v_mfma_f32_16x16x32_bf16 v[80:83], v[168:171], v[84:87], 0
	v_mfma_f32_16x16x32_bf16 v[84:87], v[184:187], v[84:87], 0
	v_mfma_f32_16x16x32_bf16 v[80:83], v[176:179], v[88:91], v[80:83]
	v_mfma_f32_16x16x32_bf16 v[84:87], v[192:195], v[88:91], v[84:87]
	v_mfma_f32_16x16x32_bf16 v[88:91], v[168:171], v[92:95], 0
	v_mfma_f32_16x16x32_bf16 v[92:95], v[184:187], v[92:95], 0
	v_mfma_f32_16x16x32_bf16 v[88:91], v[176:179], v[96:99], v[88:91]
	v_mfma_f32_16x16x32_bf16 v[92:95], v[192:195], v[96:99], v[92:95]
	v_mfma_f32_16x16x32_bf16 v[96:99], v[168:171], v[100:103], 0
	v_mfma_f32_16x16x32_bf16 v[100:103], v[184:187], v[100:103], 0
	v_mfma_f32_16x16x32_bf16 v[96:99], v[176:179], v[104:107], v[96:99]
	v_mfma_f32_16x16x32_bf16 v[100:103], v[192:195], v[104:107], v[100:103]
	s_mov_b32 m0, s62
	s_barrier
	ds_read_b128 v[104:107], v239 offset:16384
	ds_read_b128 v[132:135], v239 offset:17408
	ds_read_b128 v[136:139], v239 offset:18432
	ds_read_b128 v[148:151], v239 offset:19456
	ds_read_b128 v[156:159], v239 offset:20480
	ds_read_b128 v[164:167], v239 offset:21504
	ds_read_b128 v[172:175], v239 offset:22528
	global_load_lds_dwordx4 v204, s[56:57]
	s_mov_b32 m0, s63
	ds_read_b128 v[180:183], v239 offset:23552
	global_load_lds_dwordx4 v202, s[56:57]
	s_barrier
	s_waitcnt lgkmcnt(0)
	v_mfma_f32_16x16x32_bf16 v[112:115], v[52:55], v[104:107], 0
	v_mfma_f32_16x16x32_bf16 v[72:75], v[60:63], v[104:107], 0
	v_mfma_f32_16x16x32_bf16 v[48:51], v[52:55], v[136:139], 0
	v_mfma_f32_16x16x32_bf16 v[40:43], v[60:63], v[136:139], 0
	v_mfma_f32_16x16x32_bf16 v[32:35], v[52:55], v[156:159], 0
	v_mfma_f32_16x16x32_bf16 v[24:27], v[60:63], v[156:159], 0
	v_mfma_f32_16x16x32_bf16 v[16:19], v[52:55], v[172:175], 0
	v_mfma_f32_16x16x32_bf16 v[12:15], v[60:63], v[172:175], 0
	v_mfma_f32_16x16x32_bf16 v[112:115], v[56:59], v[132:135], v[112:115]
	v_mfma_f32_16x16x32_bf16 v[72:75], v[64:67], v[132:135], v[72:75]
	v_mfma_f32_16x16x32_bf16 v[48:51], v[56:59], v[148:151], v[48:51]
	v_mfma_f32_16x16x32_bf16 v[40:43], v[64:67], v[148:151], v[40:43]
	v_mfma_f32_16x16x32_bf16 v[32:35], v[56:59], v[164:167], v[32:35]
	v_mfma_f32_16x16x32_bf16 v[24:27], v[64:67], v[164:167], v[24:27]
	v_mfma_f32_16x16x32_bf16 v[16:19], v[56:59], v[180:183], v[16:19]
	v_mfma_f32_16x16x32_bf16 v[12:15], v[64:67], v[180:183], v[12:15]
	s_barrier
	s_add_i32 s24, s25, s60
	s_mov_b32 m0, s24
	s_add_u32 s22, s54, 0x40000
	s_addc_u32 s23, s55, 0
	global_load_lds_dwordx4 v2, s[22:23]
	s_add_i32 m0, s24, 0x2000
	s_waitcnt vmcnt(5)
	global_load_lds_dwordx4 v0, s[22:23]
	s_barrier
	v_mfma_f32_16x16x32_bf16 v[44:47], v[168:171], v[136:139], 0
	v_mfma_f32_16x16x32_bf16 v[36:39], v[184:187], v[136:139], 0
	v_mfma_f32_16x16x32_bf16 v[28:31], v[168:171], v[156:159], 0
	v_mfma_f32_16x16x32_bf16 v[20:23], v[184:187], v[156:159], 0
	v_mfma_f32_16x16x32_bf16 v[8:11], v[168:171], v[172:175], 0
	v_mfma_f32_16x16x32_bf16 v[4:7], v[184:187], v[172:175], 0
	v_mfma_f32_16x16x32_bf16 v[52:55], v[168:171], v[104:107], 0
	v_mfma_f32_16x16x32_bf16 v[56:59], v[184:187], v[104:107], 0
	v_mfma_f32_16x16x32_bf16 v[44:47], v[176:179], v[148:151], v[44:47]
	v_mfma_f32_16x16x32_bf16 v[36:39], v[192:195], v[148:151], v[36:39]
	v_mfma_f32_16x16x32_bf16 v[28:31], v[176:179], v[164:167], v[28:31]
	v_mfma_f32_16x16x32_bf16 v[20:23], v[192:195], v[164:167], v[20:23]
	v_mfma_f32_16x16x32_bf16 v[8:11], v[176:179], v[180:183], v[8:11]
	v_mfma_f32_16x16x32_bf16 v[4:7], v[192:195], v[180:183], v[4:7]
	v_mfma_f32_16x16x32_bf16 v[52:55], v[176:179], v[132:135], v[52:55]
	v_mfma_f32_16x16x32_bf16 v[56:59], v[192:195], v[132:135], v[56:59]
	s_add_i32 s24, 0, 0x18000
	s_barrier
	ds_read_b128 v[60:63], v198 offset:32768
	ds_read_b128 v[64:67], v198 offset:33792
	ds_read_b128 v[68:71], v198 offset:34816
	ds_read_b128 v[104:107], v198 offset:35840
	s_add_u32 s22, s56, 0x40000
	s_addc_u32 s23, s57, 0
	s_mov_b32 m0, s64
	ds_read_b128 v[108:111], v239 offset:32768
	ds_read_b128 v[132:135], v239 offset:33792
	ds_read_b128 v[136:139], v239 offset:34816
	ds_read_b128 v[148:151], v239 offset:35840
	ds_read_b128 v[210:213], v239 offset:36864
	ds_read_b128 v[214:217], v239 offset:37888
	ds_read_b128 v[240:243], v239 offset:38912
	global_load_lds_dwordx4 v204, s[22:23]
	s_mov_b32 m0, s65
	ds_read_b128 v[244:247], v239 offset:39936
	global_load_lds_dwordx4 v202, s[22:23]
	s_waitcnt lgkmcnt(8)
	s_barrier
	s_waitcnt lgkmcnt(0)
	v_mfma_f32_16x16x32_bf16 v[116:119], v[60:63], v[108:111], v[116:119]
	v_mfma_f32_16x16x32_bf16 v[192:195], v[64:67], v[132:135], v[116:119]
	v_mfma_f32_16x16x32_bf16 v[116:119], v[68:71], v[108:111], v[120:123]
	v_mfma_f32_16x16x32_bf16 v[184:187], v[104:107], v[132:135], v[116:119]
	v_mfma_f32_16x16x32_bf16 v[116:119], v[60:63], v[136:139], v[124:127]
	v_mfma_f32_16x16x32_bf16 v[176:179], v[64:67], v[148:151], v[116:119]
	v_mfma_f32_16x16x32_bf16 v[116:119], v[68:71], v[136:139], v[128:131]
	v_mfma_f32_16x16x32_bf16 v[168:171], v[104:107], v[148:151], v[116:119]
	v_mfma_f32_16x16x32_bf16 v[116:119], v[60:63], v[210:213], v[160:163]
	v_mfma_f32_16x16x32_bf16 v[160:163], v[64:67], v[214:217], v[116:119]
	v_mfma_f32_16x16x32_bf16 v[116:119], v[68:71], v[210:213], v[152:155]
	v_mfma_f32_16x16x32_bf16 v[152:155], v[104:107], v[214:217], v[116:119]
	v_mfma_f32_16x16x32_bf16 v[116:119], v[60:63], v[240:243], v[144:147]
	v_mfma_f32_16x16x32_bf16 v[144:147], v[64:67], v[244:247], v[116:119]
	v_mfma_f32_16x16x32_bf16 v[116:119], v[68:71], v[240:243], v[140:143]
	v_mfma_f32_16x16x32_bf16 v[140:143], v[104:107], v[244:247], v[116:119]
	s_barrier
	s_add_i32 s25, 0, 0x1c000
	s_add_i32 s22, s24, s60
	s_mov_b32 m0, s22
	ds_read_b128 v[116:119], v198 offset:49152
	ds_read_b128 v[120:123], v198 offset:50176
	ds_read_b128 v[124:127], v198 offset:51200
	s_add_u32 s98, s54, 0x80
	s_addc_u32 s99, s55, 0
	global_load_lds_dwordx4 v2, s[98:99]
	s_add_i32 m0, s22, 0x2000
	ds_read_b128 v[128:131], v198 offset:52224
	global_load_lds_dwordx4 v0, s[98:99]
	s_barrier
	s_waitcnt lgkmcnt(0)
	v_mfma_f32_16x16x32_bf16 v[76:79], v[124:127], v[108:111], v[76:79]
	v_mfma_f32_16x16x32_bf16 v[180:183], v[128:131], v[132:135], v[76:79]
	v_mfma_f32_16x16x32_bf16 v[76:79], v[116:119], v[136:139], v[80:83]
	v_mfma_f32_16x16x32_bf16 v[172:175], v[120:123], v[148:151], v[76:79]
	v_mfma_f32_16x16x32_bf16 v[76:79], v[124:127], v[136:139], v[84:87]
	v_mfma_f32_16x16x32_bf16 v[156:159], v[116:119], v[108:111], v[188:191]
	v_mfma_f32_16x16x32_bf16 v[164:167], v[128:131], v[148:151], v[76:79]
	v_mfma_f32_16x16x32_bf16 v[76:79], v[116:119], v[210:213], v[88:91]
	v_mfma_f32_16x16x32_bf16 v[188:191], v[120:123], v[132:135], v[156:159]
	v_mfma_f32_16x16x32_bf16 v[156:159], v[120:123], v[214:217], v[76:79]
	v_mfma_f32_16x16x32_bf16 v[76:79], v[124:127], v[210:213], v[92:95]
	v_mfma_f32_16x16x32_bf16 v[148:151], v[128:131], v[214:217], v[76:79]
	v_mfma_f32_16x16x32_bf16 v[76:79], v[116:119], v[240:243], v[96:99]
	v_mfma_f32_16x16x32_bf16 v[136:139], v[120:123], v[244:247], v[76:79]
	v_mfma_f32_16x16x32_bf16 v[76:79], v[124:127], v[240:243], v[100:103]
	v_mfma_f32_16x16x32_bf16 v[132:135], v[128:131], v[244:247], v[76:79]
	s_mov_b32 m0, s72
	s_barrier
	s_nop 2
	ds_read_b128 v[76:79], v239 offset:49152
	ds_read_b128 v[80:83], v239 offset:50176
	ds_read_b128 v[84:87], v239 offset:51200
	ds_read_b128 v[88:91], v239 offset:52224
	ds_read_b128 v[92:95], v239 offset:53248
	ds_read_b128 v[96:99], v239 offset:54272
	ds_read_b128 v[100:103], v239 offset:55296
	s_add_u32 s98, s56, 0x80
	s_addc_u32 s99, s57, 0
	global_load_lds_dwordx4 v204, s[98:99]
	s_mov_b32 m0, s74
	ds_read_b128 v[210:213], v239 offset:56320
	global_load_lds_dwordx4 v202, s[98:99]
	s_barrier
	s_waitcnt lgkmcnt(0)
	v_mfma_f32_16x16x32_bf16 v[108:111], v[60:63], v[76:79], v[112:115]
	v_mfma_f32_16x16x32_bf16 v[72:75], v[68:71], v[76:79], v[72:75]
	v_mfma_f32_16x16x32_bf16 v[48:51], v[60:63], v[84:87], v[48:51]
	v_mfma_f32_16x16x32_bf16 v[40:43], v[68:71], v[84:87], v[40:43]
	v_mfma_f32_16x16x32_bf16 v[32:35], v[60:63], v[92:95], v[32:35]
	v_mfma_f32_16x16x32_bf16 v[24:27], v[68:71], v[92:95], v[24:27]
	v_mfma_f32_16x16x32_bf16 v[16:19], v[60:63], v[100:103], v[16:19]
	v_mfma_f32_16x16x32_bf16 v[12:15], v[68:71], v[100:103], v[12:15]
	v_mfma_f32_16x16x32_bf16 v[112:115], v[64:67], v[80:83], v[108:111]
	v_mfma_f32_16x16x32_bf16 v[72:75], v[104:107], v[80:83], v[72:75]
	v_mfma_f32_16x16x32_bf16 v[48:51], v[64:67], v[88:91], v[48:51]
	v_mfma_f32_16x16x32_bf16 v[40:43], v[104:107], v[88:91], v[40:43]
	v_mfma_f32_16x16x32_bf16 v[32:35], v[64:67], v[96:99], v[32:35]
	v_mfma_f32_16x16x32_bf16 v[24:27], v[104:107], v[96:99], v[24:27]
	v_mfma_f32_16x16x32_bf16 v[16:19], v[64:67], v[210:213], v[16:19]
	v_mfma_f32_16x16x32_bf16 v[12:15], v[104:107], v[210:213], v[12:15]
	s_barrier
	s_add_i32 s24, s25, s60
	s_mov_b32 m0, s24
	s_add_u32 s22, s54, 0x40080
	s_addc_u32 s23, s55, 0
	global_load_lds_dwordx4 v2, s[22:23]
	s_add_i32 m0, s24, 0x2000
	s_waitcnt vmcnt(5)
	global_load_lds_dwordx4 v0, s[22:23]
	s_barrier
	v_mfma_f32_16x16x32_bf16 v[52:55], v[116:119], v[76:79], v[52:55]
	v_mfma_f32_16x16x32_bf16 v[108:111], v[120:123], v[80:83], v[52:55]
	v_mfma_f32_16x16x32_bf16 v[52:55], v[124:127], v[76:79], v[56:59]
	v_mfma_f32_16x16x32_bf16 v[44:47], v[116:119], v[84:87], v[44:47]
	v_mfma_f32_16x16x32_bf16 v[36:39], v[124:127], v[84:87], v[36:39]
	v_mfma_f32_16x16x32_bf16 v[28:31], v[116:119], v[92:95], v[28:31]
	v_mfma_f32_16x16x32_bf16 v[20:23], v[124:127], v[92:95], v[20:23]
	v_mfma_f32_16x16x32_bf16 v[8:11], v[116:119], v[100:103], v[8:11]
	v_mfma_f32_16x16x32_bf16 v[4:7], v[124:127], v[100:103], v[4:7]
	v_mfma_f32_16x16x32_bf16 v[68:71], v[128:131], v[80:83], v[52:55]
	v_mfma_f32_16x16x32_bf16 v[44:47], v[120:123], v[88:91], v[44:47]
	v_mfma_f32_16x16x32_bf16 v[36:39], v[128:131], v[88:91], v[36:39]
	v_mfma_f32_16x16x32_bf16 v[28:31], v[120:123], v[96:99], v[28:31]
	v_mfma_f32_16x16x32_bf16 v[20:23], v[128:131], v[96:99], v[20:23]
	v_mfma_f32_16x16x32_bf16 v[8:11], v[120:123], v[210:213], v[8:11]
	v_mfma_f32_16x16x32_bf16 v[4:7], v[128:131], v[210:213], v[4:7]
	s_add_i32 s21, s21, 2
	s_add_u32 s52, s52, 0x100
	s_addc_u32 s53, s53, 0
	s_add_u32 s1, s1, 0x100
	s_addc_u32 s20, s20, 0
	s_cmp_gt_u32 s21, 13
	s_barrier
	s_cbranch_scc1 .Lpeel_out_80

.Lpeel_out_80:
	v_lshl_or_b32 v210, s30, 7, v238
	s_lshl_b32 s1, s50, 8
	s_add_i32 s1, s1, s67
	v_lshlrev_b32_e32 v211, 2, v210
	v_lshlrev_b32_e32 v219, 1, v210
	v_readlane_b32 s2, v252, 4
	v_readlane_b32 s3, v252, 5
	v_readlane_b32 s20, v252, 20
	v_readlane_b32 s21, v252, 21
	v_readlane_b32 s22, v252, 2
	v_readlane_b32 s23, v252, 3
	v_readlane_b32 s24, v252, 22
	v_readlane_b32 s25, v252, 23
	v_readlane_b32 s26, v252, 24
	v_readlane_b32 s27, v252, 25
	v_readlane_b32 s50, v252, 26
	v_readlane_b32 s51, v252, 27
	v_readlane_b32 s56, v252, 28
	v_readlane_b32 s57, v252, 29
	v_readlane_b32 s98, v252, 30
	v_readlane_b32 s99, v252, 31
	v_lshl_add_u32 v240, v201, 2, s1
	v_mul_u32_u24_e32 v240, 0x1600, v240
	v_add_u32_e32 v240, v240, v219
	global_load_dwordx4 v[120:123], v211, s[2:3]
	global_load_dwordx4 v[80:83], v211, s[2:3] offset:16
	global_load_dwordx4 v[116:119], v211, s[20:21]
	global_load_dwordx4 v[76:79], v211, s[20:21] offset:16
	global_load_dwordx4 v[96:99], v211, s[22:23]
	global_load_dwordx4 v[56:59], v211, s[22:23] offset:16
	global_load_dwordx4 v[92:95], v211, s[24:25]
	global_load_dwordx4 v[52:55], v211, s[24:25] offset:16
	global_load_dwordx4 v[104:107], v211, s[26:27]
	global_load_dwordx4 v[64:67], v211, s[26:27] offset:16
	global_load_dwordx4 v[100:103], v211, s[50:51]
	global_load_dwordx4 v[60:63], v211, s[50:51] offset:16
	global_load_dwordx4 v[124:127], v211, s[56:57]
	global_load_dwordx4 v[84:87], v211, s[56:57] offset:16
	global_load_dwordx4 v[128:131], v211, s[98:99]
	global_load_dwordx4 v[88:91], v211, s[98:99] offset:16
	v_readlane_b32 s56, v254, 63
	v_readlane_b32 s57, v255, 0
	v_cmp_eq_u32_e64 s[2:3], 0, v201
	v_cmp_eq_u32_e64 s[26:27], 15, v201
	s_lshr_b32 s24, s1, 4
	s_mov_b64 exec, s[2:3]
	v_cvt_pk_bf16_f32 v212, v192, v193
	v_cvt_pk_bf16_f32 v213, v194, v195
	v_cvt_pk_bf16_f32 v214, v184, v185
	v_cvt_pk_bf16_f32 v215, v186, v187
	s_add_i32 s20, s24, 2
	s_mulk_i32 s20, 0x2c00
	s_add_u32 s22, s56, s20
	s_addc_u32 s23, s57, 0
	global_store_dwordx4 v219, v[212:215], s[22:23]
	v_cvt_pk_bf16_f32 v242, v188, v189
	v_cvt_pk_bf16_f32 v243, v190, v191
	v_cvt_pk_bf16_f32 v244, v180, v181
	v_cvt_pk_bf16_f32 v245, v182, v183
	s_add_u32 s22, s22, 0x1600
	s_addc_u32 s23, s23, 0
	global_store_dwordx4 v219, v[242:245], s[22:23]
	v_cvt_pk_bf16_f32 v246, v176, v177
	v_cvt_pk_bf16_f32 v247, v178, v179
	v_cvt_pk_bf16_f32 v248, v168, v169
	v_cvt_pk_bf16_f32 v249, v170, v171
	s_add_i32 s20, s24, 3
	s_mulk_i32 s20, 0x2c00
	s_add_u32 s22, s56, s20
	s_addc_u32 s23, s57, 0
	global_store_dwordx4 v219, v[246:249], s[22:23]
	v_cvt_pk_bf16_f32 v212, v172, v173
	v_cvt_pk_bf16_f32 v213, v174, v175
	v_cvt_pk_bf16_f32 v214, v164, v165
	v_cvt_pk_bf16_f32 v215, v166, v167
	s_add_u32 s22, s22, 0x1600
	s_addc_u32 s23, s23, 0
	global_store_dwordx4 v219, v[212:215], s[22:23]
	s_mov_b64 exec, s[26:27]
	v_cvt_pk_bf16_f32 v242, v160, v161
	v_cvt_pk_bf16_f32 v243, v162, v163
	v_cvt_pk_bf16_f32 v244, v152, v153
	v_cvt_pk_bf16_f32 v245, v154, v155
	s_add_i32 s20, s24, 0
	s_mulk_i32 s20, 0x2c00
	s_add_u32 s22, s56, s20
	s_addc_u32 s23, s57, 0
	global_store_dwordx4 v219, v[242:245], s[22:23]
	v_cvt_pk_bf16_f32 v246, v156, v157
	v_cvt_pk_bf16_f32 v247, v158, v159
	v_cvt_pk_bf16_f32 v248, v148, v149
	v_cvt_pk_bf16_f32 v249, v150, v151
	s_add_u32 s22, s22, 0x1600
	s_addc_u32 s23, s23, 0
	global_store_dwordx4 v219, v[246:249], s[22:23]
	v_cvt_pk_bf16_f32 v212, v144, v145
	v_cvt_pk_bf16_f32 v213, v146, v147
	v_cvt_pk_bf16_f32 v214, v140, v141
	v_cvt_pk_bf16_f32 v215, v142, v143
	s_add_i32 s20, s24, 1
	s_mulk_i32 s20, 0x2c00
	s_add_u32 s22, s56, s20
	s_addc_u32 s23, s57, 0
	global_store_dwordx4 v219, v[212:215], s[22:23]
	v_cvt_pk_bf16_f32 v242, v136, v137
	v_cvt_pk_bf16_f32 v243, v138, v139
	v_cvt_pk_bf16_f32 v244, v132, v133
	v_cvt_pk_bf16_f32 v245, v134, v135
	s_add_u32 s22, s22, 0x1600
	s_addc_u32 s23, s23, 0
	global_store_dwordx4 v219, v[242:245], s[22:23]
	s_mov_b64 exec, s[2:3]
	v_cvt_pk_bf16_f32 v246, v112, v113
	v_cvt_pk_bf16_f32 v247, v114, v115
	v_cvt_pk_bf16_f32 v248, v72, v73
	v_cvt_pk_bf16_f32 v249, v74, v75
	s_add_i32 s20, s24, 10
	s_mulk_i32 s20, 0x2c00
	s_add_u32 s22, s56, s20
	s_addc_u32 s23, s57, 0
	global_store_dwordx4 v219, v[246:249], s[22:23]
	v_cvt_pk_bf16_f32 v212, v108, v109
	v_cvt_pk_bf16_f32 v213, v110, v111
	v_cvt_pk_bf16_f32 v214, v68, v69
	v_cvt_pk_bf16_f32 v215, v70, v71
	s_add_u32 s22, s22, 0x1600
	s_addc_u32 s23, s23, 0
	global_store_dwordx4 v219, v[212:215], s[22:23]
	v_cvt_pk_bf16_f32 v242, v48, v49
	v_cvt_pk_bf16_f32 v243, v50, v51
	v_cvt_pk_bf16_f32 v244, v40, v41
	v_cvt_pk_bf16_f32 v245, v42, v43
	s_add_i32 s20, s24, 11
	s_mulk_i32 s20, 0x2c00
	s_add_u32 s22, s56, s20
	s_addc_u32 s23, s57, 0
	global_store_dwordx4 v219, v[242:245], s[22:23]
	v_cvt_pk_bf16_f32 v246, v44, v45
	v_cvt_pk_bf16_f32 v247, v46, v47
	v_cvt_pk_bf16_f32 v248, v36, v37
	v_cvt_pk_bf16_f32 v249, v38, v39
	s_add_u32 s22, s22, 0x1600
	s_addc_u32 s23, s23, 0
	global_store_dwordx4 v219, v[246:249], s[22:23]
	s_mov_b64 exec, s[26:27]
	v_cvt_pk_bf16_f32 v212, v32, v33
	v_cvt_pk_bf16_f32 v213, v34, v35
	v_cvt_pk_bf16_f32 v214, v24, v25
	v_cvt_pk_bf16_f32 v215, v26, v27
	s_add_i32 s20, s24, 8
	s_mulk_i32 s20, 0x2c00
	s_add_u32 s22, s56, s20
	s_addc_u32 s23, s57, 0
	global_store_dwordx4 v219, v[212:215], s[22:23]
	v_cvt_pk_bf16_f32 v242, v28, v29
	v_cvt_pk_bf16_f32 v243, v30, v31
	v_cvt_pk_bf16_f32 v244, v20, v21
	v_cvt_pk_bf16_f32 v245, v22, v23
	s_add_u32 s22, s22, 0x1600
	s_addc_u32 s23, s23, 0
	global_store_dwordx4 v219, v[242:245], s[22:23]
	v_cvt_pk_bf16_f32 v246, v16, v17
	v_cvt_pk_bf16_f32 v247, v18, v19
	v_cvt_pk_bf16_f32 v248, v12, v13
	v_cvt_pk_bf16_f32 v249, v14, v15
	s_add_i32 s20, s24, 9
	s_mulk_i32 s20, 0x2c00
	s_add_u32 s22, s56, s20
	s_addc_u32 s23, s57, 0
	global_store_dwordx4 v219, v[246:249], s[22:23]
	v_cvt_pk_bf16_f32 v212, v8, v9
	v_cvt_pk_bf16_f32 v213, v10, v11
	v_cvt_pk_bf16_f32 v214, v4, v5
	v_cvt_pk_bf16_f32 v215, v6, v7
	s_add_u32 s22, s22, 0x1600
	s_addc_u32 s23, s23, 0
	global_store_dwordx4 v219, v[212:215], s[22:23]
	s_mov_b64 exec, -1
	s_mov_b32 s50, 0xbfb8aa3b
	s_mov_b32 s51, 0xbfb8aa3b
	s_waitcnt vmcnt(16)
	v_mov_b32_dpp v198, v144 row_shr:1 row_mask:0xf bank_mask:0xf bound_ctrl:1
	v_mov_b32_dpp v199, v145 row_shr:1 row_mask:0xf bank_mask:0xf bound_ctrl:1
	v_mov_b32_dpp v214, v136 row_shr:1 row_mask:0xf bank_mask:0xf bound_ctrl:1
	v_mov_b32_dpp v215, v137 row_shr:1 row_mask:0xf bank_mask:0xf bound_ctrl:1
	v_mov_b32_dpp v212, v160 row_shr:1 row_mask:0xf bank_mask:0xf bound_ctrl:1
	v_mov_b32_dpp v213, v161 row_shr:1 row_mask:0xf bank_mask:0xf bound_ctrl:1
	v_mov_b32_dpp v216, v156 row_shr:1 row_mask:0xf bank_mask:0xf bound_ctrl:1
	v_mov_b32_dpp v217, v157 row_shr:1 row_mask:0xf bank_mask:0xf bound_ctrl:1
	v_pk_fma_f32 v[144:145], v[144:145], v[124:125], v[120:121]
	v_pk_fma_f32 v[136:137], v[136:137], v[128:129], v[116:117]
	v_pk_fma_f32 v[144:145], v[160:161], v[104:105], v[144:145]
	v_pk_fma_f32 v[136:137], v[156:157], v[100:101], v[136:137]
	v_pk_fma_f32 v[144:145], v[176:177], v[96:97], v[144:145]
	v_pk_fma_f32 v[136:137], v[172:173], v[92:93], v[136:137]
	v_pk_fma_f32 v[160:161], v[160:161], v[124:125], v[120:121]
	v_pk_fma_f32 v[156:157], v[156:157], v[128:129], v[116:117]
	v_pk_fma_f32 v[160:161], v[176:177], v[104:105], v[160:161]
	v_pk_fma_f32 v[156:157], v[172:173], v[100:101], v[156:157]
	v_pk_fma_f32 v[160:161], v[192:193], v[96:97], v[160:161]
	v_pk_fma_f32 v[156:157], v[188:189], v[92:93], v[156:157]
	v_pk_fma_f32 v[176:177], v[176:177], v[124:125], v[120:121]
	v_pk_fma_f32 v[172:173], v[172:173], v[128:129], v[116:117]
	v_pk_fma_f32 v[176:177], v[192:193], v[104:105], v[176:177]
	v_pk_fma_f32 v[172:173], v[188:189], v[100:101], v[172:173]
	v_pk_fma_f32 v[176:177], v[198:199], v[96:97], v[176:177]
	v_pk_fma_f32 v[172:173], v[214:215], v[92:93], v[172:173]
	v_pk_fma_f32 v[192:193], v[192:193], v[124:125], v[120:121]
	v_pk_fma_f32 v[188:189], v[188:189], v[128:129], v[116:117]
	v_pk_fma_f32 v[192:193], v[198:199], v[104:105], v[192:193]
	v_pk_fma_f32 v[188:189], v[214:215], v[100:101], v[188:189]
	v_pk_fma_f32 v[192:193], v[212:213], v[96:97], v[192:193]
	v_pk_fma_f32 v[188:189], v[216:217], v[92:93], v[188:189]
	v_pk_mul_f32 v[222:223], v[192:193], s[50:51]
	v_pk_mul_f32 v[242:243], v[176:177], s[50:51]
	v_pk_mul_f32 v[244:245], v[160:161], s[50:51]
	v_pk_mul_f32 v[246:247], v[144:145], s[50:51]
	v_exp_f32_e32 v222, v222
	v_exp_f32_e32 v223, v223
	v_exp_f32_e32 v242, v242
	v_exp_f32_e32 v243, v243
	v_exp_f32_e32 v244, v244
	v_exp_f32_e32 v245, v245
	v_exp_f32_e32 v246, v246
	v_exp_f32_e32 v247, v247
	v_pk_add_f32 v[222:223], v[222:223], 1.0 op_sel_hi:[1,0]
	v_pk_add_f32 v[242:243], v[242:243], 1.0 op_sel_hi:[1,0]
	v_pk_add_f32 v[244:245], v[244:245], 1.0 op_sel_hi:[1,0]
	v_pk_add_f32 v[246:247], v[246:247], 1.0 op_sel_hi:[1,0]
	v_rcp_f32_e32 v222, v222
	v_rcp_f32_e32 v223, v223
	v_rcp_f32_e32 v242, v242
	v_rcp_f32_e32 v243, v243
	v_rcp_f32_e32 v244, v244
	v_rcp_f32_e32 v245, v245
	v_rcp_f32_e32 v246, v246
	v_rcp_f32_e32 v247, v247
	v_pk_mul_f32 v[192:193], v[192:193], v[222:223]
	v_pk_mul_f32 v[176:177], v[176:177], v[242:243]
	v_pk_mul_f32 v[160:161], v[160:161], v[244:245]
	v_pk_mul_f32 v[144:145], v[144:145], v[246:247]
	v_pk_mul_f32 v[192:193], v[192:193], v[188:189]
	v_pk_mul_f32 v[176:177], v[176:177], v[172:173]
	v_pk_mul_f32 v[160:161], v[160:161], v[156:157]
	v_pk_mul_f32 v[144:145], v[144:145], v[136:137]
	v_cvt_pk_bf16_f32 v192, v192, v193
	v_cvt_pk_bf16_f32 v176, v176, v177
	v_cvt_pk_bf16_f32 v160, v160, v161
	v_cvt_pk_bf16_f32 v144, v144, v145
	v_mov_b32_dpp v198, v146 row_shr:1 row_mask:0xf bank_mask:0xf bound_ctrl:1
	v_mov_b32_dpp v199, v147 row_shr:1 row_mask:0xf bank_mask:0xf bound_ctrl:1
	v_mov_b32_dpp v214, v138 row_shr:1 row_mask:0xf bank_mask:0xf bound_ctrl:1
	v_mov_b32_dpp v215, v139 row_shr:1 row_mask:0xf bank_mask:0xf bound_ctrl:1
	v_mov_b32_dpp v212, v162 row_shr:1 row_mask:0xf bank_mask:0xf bound_ctrl:1
	v_mov_b32_dpp v213, v163 row_shr:1 row_mask:0xf bank_mask:0xf bound_ctrl:1
	v_mov_b32_dpp v216, v158 row_shr:1 row_mask:0xf bank_mask:0xf bound_ctrl:1
	v_mov_b32_dpp v217, v159 row_shr:1 row_mask:0xf bank_mask:0xf bound_ctrl:1
	v_pk_fma_f32 v[146:147], v[146:147], v[126:127], v[122:123]
	v_pk_fma_f32 v[138:139], v[138:139], v[130:131], v[118:119]
	v_pk_fma_f32 v[146:147], v[162:163], v[106:107], v[146:147]
	v_pk_fma_f32 v[138:139], v[158:159], v[102:103], v[138:139]
	v_pk_fma_f32 v[146:147], v[178:179], v[98:99], v[146:147]
	v_pk_fma_f32 v[138:139], v[174:175], v[94:95], v[138:139]
	v_pk_fma_f32 v[162:163], v[162:163], v[126:127], v[122:123]
	v_pk_fma_f32 v[158:159], v[158:159], v[130:131], v[118:119]
	v_pk_fma_f32 v[162:163], v[178:179], v[106:107], v[162:163]
	v_pk_fma_f32 v[158:159], v[174:175], v[102:103], v[158:159]
	v_pk_fma_f32 v[162:163], v[194:195], v[98:99], v[162:163]
	v_pk_fma_f32 v[158:159], v[190:191], v[94:95], v[158:159]
	v_pk_fma_f32 v[178:179], v[178:179], v[126:127], v[122:123]
	v_pk_fma_f32 v[174:175], v[174:175], v[130:131], v[118:119]
	v_pk_fma_f32 v[178:179], v[194:195], v[106:107], v[178:179]
	v_pk_fma_f32 v[174:175], v[190:191], v[102:103], v[174:175]
	v_pk_fma_f32 v[178:179], v[198:199], v[98:99], v[178:179]
	v_pk_fma_f32 v[174:175], v[214:215], v[94:95], v[174:175]
	v_pk_fma_f32 v[194:195], v[194:195], v[126:127], v[122:123]
	v_pk_fma_f32 v[190:191], v[190:191], v[130:131], v[118:119]
	v_pk_fma_f32 v[194:195], v[198:199], v[106:107], v[194:195]
	v_pk_fma_f32 v[190:191], v[214:215], v[102:103], v[190:191]
	v_pk_fma_f32 v[194:195], v[212:213], v[98:99], v[194:195]
	v_pk_fma_f32 v[190:191], v[216:217], v[94:95], v[190:191]
	v_pk_mul_f32 v[222:223], v[194:195], s[50:51]
	v_pk_mul_f32 v[242:243], v[178:179], s[50:51]
	v_pk_mul_f32 v[244:245], v[162:163], s[50:51]
	v_pk_mul_f32 v[246:247], v[146:147], s[50:51]
	v_exp_f32_e32 v222, v222
	v_exp_f32_e32 v223, v223
	v_exp_f32_e32 v242, v242
	v_exp_f32_e32 v243, v243
	v_exp_f32_e32 v244, v244
	v_exp_f32_e32 v245, v245
	v_exp_f32_e32 v246, v246
	v_exp_f32_e32 v247, v247
	v_pk_add_f32 v[222:223], v[222:223], 1.0 op_sel_hi:[1,0]
	v_pk_add_f32 v[242:243], v[242:243], 1.0 op_sel_hi:[1,0]
	v_pk_add_f32 v[244:245], v[244:245], 1.0 op_sel_hi:[1,0]
	v_pk_add_f32 v[246:247], v[246:247], 1.0 op_sel_hi:[1,0]
	v_rcp_f32_e32 v222, v222
	v_rcp_f32_e32 v223, v223
	v_rcp_f32_e32 v242, v242
	v_rcp_f32_e32 v243, v243
	v_rcp_f32_e32 v244, v244
	v_rcp_f32_e32 v245, v245
	v_rcp_f32_e32 v246, v246
	v_rcp_f32_e32 v247, v247
	v_pk_mul_f32 v[194:195], v[194:195], v[222:223]
	v_pk_mul_f32 v[178:179], v[178:179], v[242:243]
	v_pk_mul_f32 v[162:163], v[162:163], v[244:245]
	v_pk_mul_f32 v[146:147], v[146:147], v[246:247]
	v_pk_mul_f32 v[194:195], v[194:195], v[190:191]
	v_pk_mul_f32 v[178:179], v[178:179], v[174:175]
	v_pk_mul_f32 v[162:163], v[162:163], v[158:159]
	v_pk_mul_f32 v[146:147], v[146:147], v[138:139]
	v_cvt_pk_bf16_f32 v193, v194, v195
	v_cvt_pk_bf16_f32 v177, v178, v179
	v_cvt_pk_bf16_f32 v161, v162, v163
	v_cvt_pk_bf16_f32 v145, v146, v147
	v_mov_b32_dpp v198, v140 row_shr:1 row_mask:0xf bank_mask:0xf bound_ctrl:1
	v_mov_b32_dpp v199, v141 row_shr:1 row_mask:0xf bank_mask:0xf bound_ctrl:1
	v_mov_b32_dpp v214, v132 row_shr:1 row_mask:0xf bank_mask:0xf bound_ctrl:1
	v_mov_b32_dpp v215, v133 row_shr:1 row_mask:0xf bank_mask:0xf bound_ctrl:1
	v_mov_b32_dpp v212, v152 row_shr:1 row_mask:0xf bank_mask:0xf bound_ctrl:1
	v_mov_b32_dpp v213, v153 row_shr:1 row_mask:0xf bank_mask:0xf bound_ctrl:1
	v_mov_b32_dpp v216, v148 row_shr:1 row_mask:0xf bank_mask:0xf bound_ctrl:1
	v_mov_b32_dpp v217, v149 row_shr:1 row_mask:0xf bank_mask:0xf bound_ctrl:1
	v_pk_fma_f32 v[140:141], v[140:141], v[84:85], v[80:81]
	v_pk_fma_f32 v[132:133], v[132:133], v[88:89], v[76:77]
	v_pk_fma_f32 v[140:141], v[152:153], v[64:65], v[140:141]
	v_pk_fma_f32 v[132:133], v[148:149], v[60:61], v[132:133]
	v_pk_fma_f32 v[140:141], v[168:169], v[56:57], v[140:141]
	v_pk_fma_f32 v[132:133], v[164:165], v[52:53], v[132:133]
	v_pk_fma_f32 v[152:153], v[152:153], v[84:85], v[80:81]
	v_pk_fma_f32 v[148:149], v[148:149], v[88:89], v[76:77]
	v_pk_fma_f32 v[152:153], v[168:169], v[64:65], v[152:153]
	v_pk_fma_f32 v[148:149], v[164:165], v[60:61], v[148:149]
	v_pk_fma_f32 v[152:153], v[184:185], v[56:57], v[152:153]
	v_pk_fma_f32 v[148:149], v[180:181], v[52:53], v[148:149]
	v_pk_fma_f32 v[168:169], v[168:169], v[84:85], v[80:81]
	v_pk_fma_f32 v[164:165], v[164:165], v[88:89], v[76:77]
	v_pk_fma_f32 v[168:169], v[184:185], v[64:65], v[168:169]
	v_pk_fma_f32 v[164:165], v[180:181], v[60:61], v[164:165]
	v_pk_fma_f32 v[168:169], v[198:199], v[56:57], v[168:169]
	v_pk_fma_f32 v[164:165], v[214:215], v[52:53], v[164:165]
	v_pk_fma_f32 v[184:185], v[184:185], v[84:85], v[80:81]
	v_pk_fma_f32 v[180:181], v[180:181], v[88:89], v[76:77]
	v_pk_fma_f32 v[184:185], v[198:199], v[64:65], v[184:185]
	v_pk_fma_f32 v[180:181], v[214:215], v[60:61], v[180:181]
	v_pk_fma_f32 v[184:185], v[212:213], v[56:57], v[184:185]
	v_pk_fma_f32 v[180:181], v[216:217], v[52:53], v[180:181]
	v_pk_mul_f32 v[222:223], v[184:185], s[50:51]
	v_pk_mul_f32 v[242:243], v[168:169], s[50:51]
	v_pk_mul_f32 v[244:245], v[152:153], s[50:51]
	v_pk_mul_f32 v[246:247], v[140:141], s[50:51]
	v_exp_f32_e32 v222, v222
	v_exp_f32_e32 v223, v223
	v_exp_f32_e32 v242, v242
	v_exp_f32_e32 v243, v243
	v_exp_f32_e32 v244, v244
	v_exp_f32_e32 v245, v245
	v_exp_f32_e32 v246, v246
	v_exp_f32_e32 v247, v247
	v_pk_add_f32 v[222:223], v[222:223], 1.0 op_sel_hi:[1,0]
	v_pk_add_f32 v[242:243], v[242:243], 1.0 op_sel_hi:[1,0]
	v_pk_add_f32 v[244:245], v[244:245], 1.0 op_sel_hi:[1,0]
	v_pk_add_f32 v[246:247], v[246:247], 1.0 op_sel_hi:[1,0]
	v_rcp_f32_e32 v222, v222
	v_rcp_f32_e32 v223, v223
	v_rcp_f32_e32 v242, v242
	v_rcp_f32_e32 v243, v243
	v_rcp_f32_e32 v244, v244
	v_rcp_f32_e32 v245, v245
	v_rcp_f32_e32 v246, v246
	v_rcp_f32_e32 v247, v247
	v_pk_mul_f32 v[184:185], v[184:185], v[222:223]
	v_pk_mul_f32 v[168:169], v[168:169], v[242:243]
	v_pk_mul_f32 v[152:153], v[152:153], v[244:245]
	v_pk_mul_f32 v[140:141], v[140:141], v[246:247]
	v_pk_mul_f32 v[184:185], v[184:185], v[180:181]
	v_pk_mul_f32 v[168:169], v[168:169], v[164:165]
	v_pk_mul_f32 v[152:153], v[152:153], v[148:149]
	v_pk_mul_f32 v[140:141], v[140:141], v[132:133]
	v_cvt_pk_bf16_f32 v194, v184, v185
	v_cvt_pk_bf16_f32 v178, v168, v169
	v_cvt_pk_bf16_f32 v162, v152, v153
	v_cvt_pk_bf16_f32 v146, v140, v141
	v_mov_b32_dpp v198, v142 row_shr:1 row_mask:0xf bank_mask:0xf bound_ctrl:1
	v_mov_b32_dpp v199, v143 row_shr:1 row_mask:0xf bank_mask:0xf bound_ctrl:1
	v_mov_b32_dpp v214, v134 row_shr:1 row_mask:0xf bank_mask:0xf bound_ctrl:1
	v_mov_b32_dpp v215, v135 row_shr:1 row_mask:0xf bank_mask:0xf bound_ctrl:1
	v_mov_b32_dpp v212, v154 row_shr:1 row_mask:0xf bank_mask:0xf bound_ctrl:1
	v_mov_b32_dpp v213, v155 row_shr:1 row_mask:0xf bank_mask:0xf bound_ctrl:1
	v_mov_b32_dpp v216, v150 row_shr:1 row_mask:0xf bank_mask:0xf bound_ctrl:1
	v_mov_b32_dpp v217, v151 row_shr:1 row_mask:0xf bank_mask:0xf bound_ctrl:1
	v_pk_fma_f32 v[142:143], v[142:143], v[86:87], v[82:83]
	v_pk_fma_f32 v[134:135], v[134:135], v[90:91], v[78:79]
	v_pk_fma_f32 v[142:143], v[154:155], v[66:67], v[142:143]
	v_pk_fma_f32 v[134:135], v[150:151], v[62:63], v[134:135]
	v_pk_fma_f32 v[142:143], v[170:171], v[58:59], v[142:143]
	v_pk_fma_f32 v[134:135], v[166:167], v[54:55], v[134:135]
	v_pk_fma_f32 v[154:155], v[154:155], v[86:87], v[82:83]
	v_pk_fma_f32 v[150:151], v[150:151], v[90:91], v[78:79]
	v_pk_fma_f32 v[154:155], v[170:171], v[66:67], v[154:155]
	v_pk_fma_f32 v[150:151], v[166:167], v[62:63], v[150:151]
	v_pk_fma_f32 v[154:155], v[186:187], v[58:59], v[154:155]
	v_pk_fma_f32 v[150:151], v[182:183], v[54:55], v[150:151]
	v_pk_fma_f32 v[170:171], v[170:171], v[86:87], v[82:83]
	v_pk_fma_f32 v[166:167], v[166:167], v[90:91], v[78:79]
	v_pk_fma_f32 v[170:171], v[186:187], v[66:67], v[170:171]
	v_pk_fma_f32 v[166:167], v[182:183], v[62:63], v[166:167]
	v_pk_fma_f32 v[170:171], v[198:199], v[58:59], v[170:171]
	v_pk_fma_f32 v[166:167], v[214:215], v[54:55], v[166:167]
	v_pk_fma_f32 v[186:187], v[186:187], v[86:87], v[82:83]
	v_pk_fma_f32 v[182:183], v[182:183], v[90:91], v[78:79]
	v_pk_fma_f32 v[186:187], v[198:199], v[66:67], v[186:187]
	v_pk_fma_f32 v[182:183], v[214:215], v[62:63], v[182:183]
	v_pk_fma_f32 v[186:187], v[212:213], v[58:59], v[186:187]
	v_pk_fma_f32 v[182:183], v[216:217], v[54:55], v[182:183]
	v_pk_mul_f32 v[222:223], v[186:187], s[50:51]
	v_pk_mul_f32 v[242:243], v[170:171], s[50:51]
	v_pk_mul_f32 v[244:245], v[154:155], s[50:51]
	v_pk_mul_f32 v[246:247], v[142:143], s[50:51]
	v_exp_f32_e32 v222, v222
	v_exp_f32_e32 v223, v223
	v_exp_f32_e32 v242, v242
	v_exp_f32_e32 v243, v243
	v_exp_f32_e32 v244, v244
	v_exp_f32_e32 v245, v245
	v_exp_f32_e32 v246, v246
	v_exp_f32_e32 v247, v247
	v_pk_add_f32 v[222:223], v[222:223], 1.0 op_sel_hi:[1,0]
	v_pk_add_f32 v[242:243], v[242:243], 1.0 op_sel_hi:[1,0]
	v_pk_add_f32 v[244:245], v[244:245], 1.0 op_sel_hi:[1,0]
	v_pk_add_f32 v[246:247], v[246:247], 1.0 op_sel_hi:[1,0]
	v_rcp_f32_e32 v222, v222
	v_rcp_f32_e32 v223, v223
	v_rcp_f32_e32 v242, v242
	v_rcp_f32_e32 v243, v243
	v_rcp_f32_e32 v244, v244
	v_rcp_f32_e32 v245, v245
	v_rcp_f32_e32 v246, v246
	v_rcp_f32_e32 v247, v247
	v_pk_mul_f32 v[186:187], v[186:187], v[222:223]
	v_pk_mul_f32 v[170:171], v[170:171], v[242:243]
	v_pk_mul_f32 v[154:155], v[154:155], v[244:245]
	v_pk_mul_f32 v[142:143], v[142:143], v[246:247]
	v_pk_mul_f32 v[186:187], v[186:187], v[182:183]
	v_pk_mul_f32 v[170:171], v[170:171], v[166:167]
	v_pk_mul_f32 v[154:155], v[154:155], v[150:151]
	v_pk_mul_f32 v[142:143], v[142:143], v[134:135]
	v_cvt_pk_bf16_f32 v195, v186, v187
	v_cvt_pk_bf16_f32 v179, v170, v171
	v_cvt_pk_bf16_f32 v163, v154, v155
	v_cvt_pk_bf16_f32 v147, v142, v143
	s_mov_b64 s[20:21], s[82:83]
	global_store_dwordx4 v240, v[192:195], s[20:21]
	s_add_u32 s20, s82, 0x1600
	s_addc_u32 s21, s83, 0
	global_store_dwordx4 v240, v[176:179], s[20:21]
	s_add_u32 s20, s82, 0x2c00
	s_addc_u32 s21, s83, 0
	global_store_dwordx4 v240, v[160:163], s[20:21]
	s_add_u32 s20, s82, 0x4200
	s_addc_u32 s21, s83, 0
	global_store_dwordx4 v240, v[144:147], s[20:21]
	v_mov_b32_dpp v198, v16 row_shr:1 row_mask:0xf bank_mask:0xf bound_ctrl:1
	v_mov_b32_dpp v199, v17 row_shr:1 row_mask:0xf bank_mask:0xf bound_ctrl:1
	v_mov_b32_dpp v214, v8 row_shr:1 row_mask:0xf bank_mask:0xf bound_ctrl:1
	v_mov_b32_dpp v215, v9 row_shr:1 row_mask:0xf bank_mask:0xf bound_ctrl:1
	v_mov_b32_dpp v212, v32 row_shr:1 row_mask:0xf bank_mask:0xf bound_ctrl:1
	v_mov_b32_dpp v213, v33 row_shr:1 row_mask:0xf bank_mask:0xf bound_ctrl:1
	v_mov_b32_dpp v216, v28 row_shr:1 row_mask:0xf bank_mask:0xf bound_ctrl:1
	v_mov_b32_dpp v217, v29 row_shr:1 row_mask:0xf bank_mask:0xf bound_ctrl:1
	v_pk_fma_f32 v[16:17], v[16:17], v[124:125], v[120:121]
	v_pk_fma_f32 v[8:9], v[8:9], v[128:129], v[116:117]
	v_pk_fma_f32 v[16:17], v[32:33], v[104:105], v[16:17]
	v_pk_fma_f32 v[8:9], v[28:29], v[100:101], v[8:9]
	v_pk_fma_f32 v[16:17], v[48:49], v[96:97], v[16:17]
	v_pk_fma_f32 v[8:9], v[44:45], v[92:93], v[8:9]
	v_pk_fma_f32 v[32:33], v[32:33], v[124:125], v[120:121]
	v_pk_fma_f32 v[28:29], v[28:29], v[128:129], v[116:117]
	v_pk_fma_f32 v[32:33], v[48:49], v[104:105], v[32:33]
	v_pk_fma_f32 v[28:29], v[44:45], v[100:101], v[28:29]
	v_pk_fma_f32 v[32:33], v[112:113], v[96:97], v[32:33]
	v_pk_fma_f32 v[28:29], v[108:109], v[92:93], v[28:29]
	v_pk_fma_f32 v[48:49], v[48:49], v[124:125], v[120:121]
	v_pk_fma_f32 v[44:45], v[44:45], v[128:129], v[116:117]
	v_pk_fma_f32 v[48:49], v[112:113], v[104:105], v[48:49]
	v_pk_fma_f32 v[44:45], v[108:109], v[100:101], v[44:45]
	v_pk_fma_f32 v[48:49], v[198:199], v[96:97], v[48:49]
	v_pk_fma_f32 v[44:45], v[214:215], v[92:93], v[44:45]
	v_pk_fma_f32 v[112:113], v[112:113], v[124:125], v[120:121]
	v_pk_fma_f32 v[108:109], v[108:109], v[128:129], v[116:117]
	v_pk_fma_f32 v[112:113], v[198:199], v[104:105], v[112:113]
	v_pk_fma_f32 v[108:109], v[214:215], v[100:101], v[108:109]
	v_pk_fma_f32 v[112:113], v[212:213], v[96:97], v[112:113]
	v_pk_fma_f32 v[108:109], v[216:217], v[92:93], v[108:109]
	v_pk_mul_f32 v[222:223], v[112:113], s[50:51]
	v_pk_mul_f32 v[242:243], v[48:49], s[50:51]
	v_pk_mul_f32 v[244:245], v[32:33], s[50:51]
	v_pk_mul_f32 v[246:247], v[16:17], s[50:51]
	v_exp_f32_e32 v222, v222
	v_exp_f32_e32 v223, v223
	v_exp_f32_e32 v242, v242
	v_exp_f32_e32 v243, v243
	v_exp_f32_e32 v244, v244
	v_exp_f32_e32 v245, v245
	v_exp_f32_e32 v246, v246
	v_exp_f32_e32 v247, v247
	v_pk_add_f32 v[222:223], v[222:223], 1.0 op_sel_hi:[1,0]
	v_pk_add_f32 v[242:243], v[242:243], 1.0 op_sel_hi:[1,0]
	v_pk_add_f32 v[244:245], v[244:245], 1.0 op_sel_hi:[1,0]
	v_pk_add_f32 v[246:247], v[246:247], 1.0 op_sel_hi:[1,0]
	v_rcp_f32_e32 v222, v222
	v_rcp_f32_e32 v223, v223
	v_rcp_f32_e32 v242, v242
	v_rcp_f32_e32 v243, v243
	v_rcp_f32_e32 v244, v244
	v_rcp_f32_e32 v245, v245
	v_rcp_f32_e32 v246, v246
	v_rcp_f32_e32 v247, v247
	v_pk_mul_f32 v[112:113], v[112:113], v[222:223]
	v_pk_mul_f32 v[48:49], v[48:49], v[242:243]
	v_pk_mul_f32 v[32:33], v[32:33], v[244:245]
	v_pk_mul_f32 v[16:17], v[16:17], v[246:247]
	v_pk_mul_f32 v[112:113], v[112:113], v[108:109]
	v_pk_mul_f32 v[48:49], v[48:49], v[44:45]
	v_pk_mul_f32 v[32:33], v[32:33], v[28:29]
	v_pk_mul_f32 v[16:17], v[16:17], v[8:9]
	v_cvt_pk_bf16_f32 v112, v112, v113
	v_cvt_pk_bf16_f32 v48, v48, v49
	v_cvt_pk_bf16_f32 v32, v32, v33
	v_cvt_pk_bf16_f32 v16, v16, v17
	v_mov_b32_dpp v198, v18 row_shr:1 row_mask:0xf bank_mask:0xf bound_ctrl:1
	v_mov_b32_dpp v199, v19 row_shr:1 row_mask:0xf bank_mask:0xf bound_ctrl:1
	v_mov_b32_dpp v214, v10 row_shr:1 row_mask:0xf bank_mask:0xf bound_ctrl:1
	v_mov_b32_dpp v215, v11 row_shr:1 row_mask:0xf bank_mask:0xf bound_ctrl:1
	v_mov_b32_dpp v212, v34 row_shr:1 row_mask:0xf bank_mask:0xf bound_ctrl:1
	v_mov_b32_dpp v213, v35 row_shr:1 row_mask:0xf bank_mask:0xf bound_ctrl:1
	v_mov_b32_dpp v216, v30 row_shr:1 row_mask:0xf bank_mask:0xf bound_ctrl:1
	v_mov_b32_dpp v217, v31 row_shr:1 row_mask:0xf bank_mask:0xf bound_ctrl:1
	v_pk_fma_f32 v[18:19], v[18:19], v[126:127], v[122:123]
	v_pk_fma_f32 v[10:11], v[10:11], v[130:131], v[118:119]
	v_pk_fma_f32 v[18:19], v[34:35], v[106:107], v[18:19]
	v_pk_fma_f32 v[10:11], v[30:31], v[102:103], v[10:11]
	v_pk_fma_f32 v[18:19], v[50:51], v[98:99], v[18:19]
	v_pk_fma_f32 v[10:11], v[46:47], v[94:95], v[10:11]
	v_pk_fma_f32 v[34:35], v[34:35], v[126:127], v[122:123]
	v_pk_fma_f32 v[30:31], v[30:31], v[130:131], v[118:119]
	v_pk_fma_f32 v[34:35], v[50:51], v[106:107], v[34:35]
	v_pk_fma_f32 v[30:31], v[46:47], v[102:103], v[30:31]
	v_pk_fma_f32 v[34:35], v[114:115], v[98:99], v[34:35]
	v_pk_fma_f32 v[30:31], v[110:111], v[94:95], v[30:31]
	v_pk_fma_f32 v[50:51], v[50:51], v[126:127], v[122:123]
	v_pk_fma_f32 v[46:47], v[46:47], v[130:131], v[118:119]
	v_pk_fma_f32 v[50:51], v[114:115], v[106:107], v[50:51]
	v_pk_fma_f32 v[46:47], v[110:111], v[102:103], v[46:47]
	v_pk_fma_f32 v[50:51], v[198:199], v[98:99], v[50:51]
	v_pk_fma_f32 v[46:47], v[214:215], v[94:95], v[46:47]
	v_pk_fma_f32 v[114:115], v[114:115], v[126:127], v[122:123]
	v_pk_fma_f32 v[110:111], v[110:111], v[130:131], v[118:119]
	v_pk_fma_f32 v[114:115], v[198:199], v[106:107], v[114:115]
	v_pk_fma_f32 v[110:111], v[214:215], v[102:103], v[110:111]
	v_pk_fma_f32 v[114:115], v[212:213], v[98:99], v[114:115]
	v_pk_fma_f32 v[110:111], v[216:217], v[94:95], v[110:111]
	v_pk_mul_f32 v[222:223], v[114:115], s[50:51]
	v_pk_mul_f32 v[242:243], v[50:51], s[50:51]
	v_pk_mul_f32 v[244:245], v[34:35], s[50:51]
	v_pk_mul_f32 v[246:247], v[18:19], s[50:51]
	v_exp_f32_e32 v222, v222
	v_exp_f32_e32 v223, v223
	v_exp_f32_e32 v242, v242
	v_exp_f32_e32 v243, v243
	v_exp_f32_e32 v244, v244
	v_exp_f32_e32 v245, v245
	v_exp_f32_e32 v246, v246
	v_exp_f32_e32 v247, v247
	v_pk_add_f32 v[222:223], v[222:223], 1.0 op_sel_hi:[1,0]
	v_pk_add_f32 v[242:243], v[242:243], 1.0 op_sel_hi:[1,0]
	v_pk_add_f32 v[244:245], v[244:245], 1.0 op_sel_hi:[1,0]
	v_pk_add_f32 v[246:247], v[246:247], 1.0 op_sel_hi:[1,0]
	v_rcp_f32_e32 v222, v222
	v_rcp_f32_e32 v223, v223
	v_rcp_f32_e32 v242, v242
	v_rcp_f32_e32 v243, v243
	v_rcp_f32_e32 v244, v244
	v_rcp_f32_e32 v245, v245
	v_rcp_f32_e32 v246, v246
	v_rcp_f32_e32 v247, v247
	v_pk_mul_f32 v[114:115], v[114:115], v[222:223]
	v_pk_mul_f32 v[50:51], v[50:51], v[242:243]
	v_pk_mul_f32 v[34:35], v[34:35], v[244:245]
	v_pk_mul_f32 v[18:19], v[18:19], v[246:247]
	v_pk_mul_f32 v[114:115], v[114:115], v[110:111]
	v_pk_mul_f32 v[50:51], v[50:51], v[46:47]
	v_pk_mul_f32 v[34:35], v[34:35], v[30:31]
	v_pk_mul_f32 v[18:19], v[18:19], v[10:11]
	v_cvt_pk_bf16_f32 v113, v114, v115
	v_cvt_pk_bf16_f32 v49, v50, v51
	v_cvt_pk_bf16_f32 v33, v34, v35
	v_cvt_pk_bf16_f32 v17, v18, v19
	v_mov_b32_dpp v198, v12 row_shr:1 row_mask:0xf bank_mask:0xf bound_ctrl:1
	v_mov_b32_dpp v199, v13 row_shr:1 row_mask:0xf bank_mask:0xf bound_ctrl:1
	v_mov_b32_dpp v214, v4 row_shr:1 row_mask:0xf bank_mask:0xf bound_ctrl:1
	v_mov_b32_dpp v215, v5 row_shr:1 row_mask:0xf bank_mask:0xf bound_ctrl:1
	v_mov_b32_dpp v212, v24 row_shr:1 row_mask:0xf bank_mask:0xf bound_ctrl:1
	v_mov_b32_dpp v213, v25 row_shr:1 row_mask:0xf bank_mask:0xf bound_ctrl:1
	v_mov_b32_dpp v216, v20 row_shr:1 row_mask:0xf bank_mask:0xf bound_ctrl:1
	v_mov_b32_dpp v217, v21 row_shr:1 row_mask:0xf bank_mask:0xf bound_ctrl:1
	v_pk_fma_f32 v[12:13], v[12:13], v[84:85], v[80:81]
	v_pk_fma_f32 v[4:5], v[4:5], v[88:89], v[76:77]
	v_pk_fma_f32 v[12:13], v[24:25], v[64:65], v[12:13]
	v_pk_fma_f32 v[4:5], v[20:21], v[60:61], v[4:5]
	v_pk_fma_f32 v[12:13], v[40:41], v[56:57], v[12:13]
	v_pk_fma_f32 v[4:5], v[36:37], v[52:53], v[4:5]
	v_pk_fma_f32 v[24:25], v[24:25], v[84:85], v[80:81]
	v_pk_fma_f32 v[20:21], v[20:21], v[88:89], v[76:77]
	v_pk_fma_f32 v[24:25], v[40:41], v[64:65], v[24:25]
	v_pk_fma_f32 v[20:21], v[36:37], v[60:61], v[20:21]
	v_pk_fma_f32 v[24:25], v[72:73], v[56:57], v[24:25]
	v_pk_fma_f32 v[20:21], v[68:69], v[52:53], v[20:21]
	v_pk_fma_f32 v[40:41], v[40:41], v[84:85], v[80:81]
	v_pk_fma_f32 v[36:37], v[36:37], v[88:89], v[76:77]
	v_pk_fma_f32 v[40:41], v[72:73], v[64:65], v[40:41]
	v_pk_fma_f32 v[36:37], v[68:69], v[60:61], v[36:37]
	v_pk_fma_f32 v[40:41], v[198:199], v[56:57], v[40:41]
	v_pk_fma_f32 v[36:37], v[214:215], v[52:53], v[36:37]
	v_pk_fma_f32 v[72:73], v[72:73], v[84:85], v[80:81]
	v_pk_fma_f32 v[68:69], v[68:69], v[88:89], v[76:77]
	v_pk_fma_f32 v[72:73], v[198:199], v[64:65], v[72:73]
	v_pk_fma_f32 v[68:69], v[214:215], v[60:61], v[68:69]
	v_pk_fma_f32 v[72:73], v[212:213], v[56:57], v[72:73]
	v_pk_fma_f32 v[68:69], v[216:217], v[52:53], v[68:69]
	v_pk_mul_f32 v[222:223], v[72:73], s[50:51]
	v_pk_mul_f32 v[242:243], v[40:41], s[50:51]
	v_pk_mul_f32 v[244:245], v[24:25], s[50:51]
	v_pk_mul_f32 v[246:247], v[12:13], s[50:51]
	v_exp_f32_e32 v222, v222
	v_exp_f32_e32 v223, v223
	v_exp_f32_e32 v242, v242
	v_exp_f32_e32 v243, v243
	v_exp_f32_e32 v244, v244
	v_exp_f32_e32 v245, v245
	v_exp_f32_e32 v246, v246
	v_exp_f32_e32 v247, v247
	v_pk_add_f32 v[222:223], v[222:223], 1.0 op_sel_hi:[1,0]
	v_pk_add_f32 v[242:243], v[242:243], 1.0 op_sel_hi:[1,0]
	v_pk_add_f32 v[244:245], v[244:245], 1.0 op_sel_hi:[1,0]
	v_pk_add_f32 v[246:247], v[246:247], 1.0 op_sel_hi:[1,0]
	v_rcp_f32_e32 v222, v222
	v_rcp_f32_e32 v223, v223
	v_rcp_f32_e32 v242, v242
	v_rcp_f32_e32 v243, v243
	v_rcp_f32_e32 v244, v244
	v_rcp_f32_e32 v245, v245
	v_rcp_f32_e32 v246, v246
	v_rcp_f32_e32 v247, v247
	v_pk_mul_f32 v[72:73], v[72:73], v[222:223]
	v_pk_mul_f32 v[40:41], v[40:41], v[242:243]
	v_pk_mul_f32 v[24:25], v[24:25], v[244:245]
	v_pk_mul_f32 v[12:13], v[12:13], v[246:247]
	v_pk_mul_f32 v[72:73], v[72:73], v[68:69]
	v_pk_mul_f32 v[40:41], v[40:41], v[36:37]
	v_pk_mul_f32 v[24:25], v[24:25], v[20:21]
	v_pk_mul_f32 v[12:13], v[12:13], v[4:5]
	v_cvt_pk_bf16_f32 v114, v72, v73
	v_cvt_pk_bf16_f32 v50, v40, v41
	v_cvt_pk_bf16_f32 v34, v24, v25
	v_cvt_pk_bf16_f32 v18, v12, v13
	v_mov_b32_dpp v198, v14 row_shr:1 row_mask:0xf bank_mask:0xf bound_ctrl:1
	v_mov_b32_dpp v199, v15 row_shr:1 row_mask:0xf bank_mask:0xf bound_ctrl:1
	v_mov_b32_dpp v214, v6 row_shr:1 row_mask:0xf bank_mask:0xf bound_ctrl:1
	v_mov_b32_dpp v215, v7 row_shr:1 row_mask:0xf bank_mask:0xf bound_ctrl:1
	v_mov_b32_dpp v212, v26 row_shr:1 row_mask:0xf bank_mask:0xf bound_ctrl:1
	v_mov_b32_dpp v213, v27 row_shr:1 row_mask:0xf bank_mask:0xf bound_ctrl:1
	v_mov_b32_dpp v216, v22 row_shr:1 row_mask:0xf bank_mask:0xf bound_ctrl:1
	v_mov_b32_dpp v217, v23 row_shr:1 row_mask:0xf bank_mask:0xf bound_ctrl:1
	v_pk_fma_f32 v[14:15], v[14:15], v[86:87], v[82:83]
	v_pk_fma_f32 v[6:7], v[6:7], v[90:91], v[78:79]
	v_pk_fma_f32 v[14:15], v[26:27], v[66:67], v[14:15]
	v_pk_fma_f32 v[6:7], v[22:23], v[62:63], v[6:7]
	v_pk_fma_f32 v[14:15], v[42:43], v[58:59], v[14:15]
	v_pk_fma_f32 v[6:7], v[38:39], v[54:55], v[6:7]
	v_pk_fma_f32 v[26:27], v[26:27], v[86:87], v[82:83]
	v_pk_fma_f32 v[22:23], v[22:23], v[90:91], v[78:79]
	v_pk_fma_f32 v[26:27], v[42:43], v[66:67], v[26:27]
	v_pk_fma_f32 v[22:23], v[38:39], v[62:63], v[22:23]
	v_pk_fma_f32 v[26:27], v[74:75], v[58:59], v[26:27]
	v_pk_fma_f32 v[22:23], v[70:71], v[54:55], v[22:23]
	v_pk_fma_f32 v[42:43], v[42:43], v[86:87], v[82:83]
	v_pk_fma_f32 v[38:39], v[38:39], v[90:91], v[78:79]
	v_pk_fma_f32 v[42:43], v[74:75], v[66:67], v[42:43]
	v_pk_fma_f32 v[38:39], v[70:71], v[62:63], v[38:39]
	v_pk_fma_f32 v[42:43], v[198:199], v[58:59], v[42:43]
	v_pk_fma_f32 v[38:39], v[214:215], v[54:55], v[38:39]
	v_pk_fma_f32 v[74:75], v[74:75], v[86:87], v[82:83]
	v_pk_fma_f32 v[70:71], v[70:71], v[90:91], v[78:79]
	v_pk_fma_f32 v[74:75], v[198:199], v[66:67], v[74:75]
	v_pk_fma_f32 v[70:71], v[214:215], v[62:63], v[70:71]
	v_pk_fma_f32 v[74:75], v[212:213], v[58:59], v[74:75]
	v_pk_fma_f32 v[70:71], v[216:217], v[54:55], v[70:71]
	v_pk_mul_f32 v[222:223], v[74:75], s[50:51]
	v_pk_mul_f32 v[242:243], v[42:43], s[50:51]
	v_pk_mul_f32 v[244:245], v[26:27], s[50:51]
	v_pk_mul_f32 v[246:247], v[14:15], s[50:51]
	v_exp_f32_e32 v222, v222
	v_exp_f32_e32 v223, v223
	v_exp_f32_e32 v242, v242
	v_exp_f32_e32 v243, v243
	v_exp_f32_e32 v244, v244
	v_exp_f32_e32 v245, v245
	v_exp_f32_e32 v246, v246
	v_exp_f32_e32 v247, v247
	v_pk_add_f32 v[222:223], v[222:223], 1.0 op_sel_hi:[1,0]
	v_pk_add_f32 v[242:243], v[242:243], 1.0 op_sel_hi:[1,0]
	v_pk_add_f32 v[244:245], v[244:245], 1.0 op_sel_hi:[1,0]
	v_pk_add_f32 v[246:247], v[246:247], 1.0 op_sel_hi:[1,0]
	v_rcp_f32_e32 v222, v222
	v_rcp_f32_e32 v223, v223
	v_rcp_f32_e32 v242, v242
	v_rcp_f32_e32 v243, v243
	v_rcp_f32_e32 v244, v244
	v_rcp_f32_e32 v245, v245
	v_rcp_f32_e32 v246, v246
	v_rcp_f32_e32 v247, v247
	v_pk_mul_f32 v[74:75], v[74:75], v[222:223]
	v_pk_mul_f32 v[42:43], v[42:43], v[242:243]
	v_pk_mul_f32 v[26:27], v[26:27], v[244:245]
	v_pk_mul_f32 v[14:15], v[14:15], v[246:247]
	v_pk_mul_f32 v[74:75], v[74:75], v[70:71]
	v_pk_mul_f32 v[42:43], v[42:43], v[38:39]
	v_pk_mul_f32 v[26:27], v[26:27], v[22:23]
	v_pk_mul_f32 v[14:15], v[14:15], v[6:7]
	v_cvt_pk_bf16_f32 v115, v74, v75
	v_cvt_pk_bf16_f32 v51, v42, v43
	v_cvt_pk_bf16_f32 v35, v26, v27
	v_cvt_pk_bf16_f32 v19, v14, v15
	s_add_u32 s20, s82, 0xb0000
	s_addc_u32 s21, s83, 0
	global_store_dwordx4 v240, v[112:115], s[20:21]
	s_add_u32 s20, s82, 0xb1600
	s_addc_u32 s21, s83, 0
	global_store_dwordx4 v240, v[48:51], s[20:21]
	s_add_u32 s20, s82, 0xb2c00
	s_addc_u32 s21, s83, 0
	global_store_dwordx4 v240, v[32:35], s[20:21]
	s_add_u32 s20, s82, 0xb4200
	s_addc_u32 s21, s83, 0
	global_store_dwordx4 v240, v[16:19], s[20:21]
	s_mov_b64 s[50:51], -1
	s_branch .LBB0_76

.LBB0_135:
	s_add_u32 s48, s48, 0x40080
	s_addc_u32 s49, s49, 0
	s_add_u32 s20, s50, 0x100
	s_addc_u32 s21, s51, 0
	s_mov_b32 s22, -2
	v_add_u32_e32 v194, 0x10000, v143
	s_add_u32 s23, s48, 0xfffc0080
	s_addc_u32 s24, s49, -1
	s_add_i32 s25, 0, 0x10000
	ds_read_b128 v[146:149], v194
	ds_read_b128 v[150:153], v194 offset:1024
	ds_read_b128 v[154:157], v194 offset:2048
	ds_read_b128 v[158:161], v194 offset:3072
	s_cmp_eq_u32 s22, 12
	s_cselect_b32 s53, s45, s24
	s_cselect_b32 s52, s44, s23
	s_cselect_b32 s51, s47, s21
	s_cselect_b32 s50, s46, s20
	s_add_i32 m0, s54, 0xc000
	ds_read_b128 v[162:165], v144
	ds_read_b128 v[166:169], v144 offset:1024
	ds_read_b128 v[170:173], v144 offset:2048
	ds_read_b128 v[174:177], v144 offset:3072
	ds_read_b128 v[178:181], v144 offset:4096
	ds_read_b128 v[182:185], v144 offset:5120
	ds_read_b128 v[186:189], v144 offset:6144
	global_load_lds_dwordx4 v138, s[48:49]
	s_add_i32 m0, s54, 0xe000
	ds_read_b128 v[190:193], v144 offset:7168
	global_load_lds_dwordx4 v140, s[48:49]
	s_waitcnt lgkmcnt(8)
	s_barrier
	s_waitcnt lgkmcnt(0)
	v_mfma_f32_16x16x32_bf16 v[128:131], v[146:149], v[162:165], 0
	v_mfma_f32_16x16x32_bf16 v[124:127], v[154:157], v[162:165], 0
	v_mfma_f32_16x16x32_bf16 v[120:123], v[146:149], v[170:173], 0
	v_mfma_f32_16x16x32_bf16 v[116:119], v[154:157], v[170:173], 0
	v_mfma_f32_16x16x32_bf16 v[104:107], v[146:149], v[178:181], 0
	v_mfma_f32_16x16x32_bf16 v[100:103], v[154:157], v[178:181], 0
	v_mfma_f32_16x16x32_bf16 v[88:91], v[146:149], v[186:189], 0
	v_mfma_f32_16x16x32_bf16 v[84:87], v[154:157], v[186:189], 0
	v_mfma_f32_16x16x32_bf16 v[128:131], v[150:153], v[166:169], v[128:131]
	v_mfma_f32_16x16x32_bf16 v[124:127], v[158:161], v[166:169], v[124:127]
	v_mfma_f32_16x16x32_bf16 v[120:123], v[150:153], v[174:177], v[120:123]
	v_mfma_f32_16x16x32_bf16 v[116:119], v[158:161], v[174:177], v[116:119]
	v_mfma_f32_16x16x32_bf16 v[104:107], v[150:153], v[182:185], v[104:107]
	v_mfma_f32_16x16x32_bf16 v[100:103], v[158:161], v[182:185], v[100:103]
	v_mfma_f32_16x16x32_bf16 v[88:91], v[150:153], v[190:193], v[88:91]
	v_mfma_f32_16x16x32_bf16 v[84:87], v[158:161], v[190:193], v[84:87]
	s_barrier
	s_add_i32 s23, 0, 0x14000
	s_add_i32 s24, s25, s37
	s_mov_b32 m0, s24
	ds_read_b128 v[202:205], v194 offset:16384
	ds_read_b128 v[206:209], v194 offset:17408
	ds_read_b128 v[210:213], v194 offset:18432
	global_load_lds_dwordx4 v132, s[50:51]
	s_add_i32 m0, s24, 0x2000
	ds_read_b128 v[214:217], v194 offset:19456
	global_load_lds_dwordx4 v136, s[50:51]
	s_barrier
	s_waitcnt lgkmcnt(0)
	v_mfma_f32_16x16x32_bf16 v[112:115], v[202:205], v[162:165], 0
	v_mfma_f32_16x16x32_bf16 v[108:111], v[210:213], v[162:165], 0
	v_mfma_f32_16x16x32_bf16 v[96:99], v[202:205], v[170:173], 0
	v_mfma_f32_16x16x32_bf16 v[92:95], v[210:213], v[170:173], 0
	v_mfma_f32_16x16x32_bf16 v[80:83], v[202:205], v[178:181], 0
	v_mfma_f32_16x16x32_bf16 v[76:79], v[210:213], v[178:181], 0
	v_mfma_f32_16x16x32_bf16 v[72:75], v[202:205], v[186:189], 0
	v_mfma_f32_16x16x32_bf16 v[68:71], v[210:213], v[186:189], 0
	v_mfma_f32_16x16x32_bf16 v[112:115], v[206:209], v[166:169], v[112:115]
	v_mfma_f32_16x16x32_bf16 v[108:111], v[214:217], v[166:169], v[108:111]
	v_mfma_f32_16x16x32_bf16 v[96:99], v[206:209], v[174:177], v[96:99]
	v_mfma_f32_16x16x32_bf16 v[92:95], v[214:217], v[174:177], v[92:95]
	v_mfma_f32_16x16x32_bf16 v[80:83], v[206:209], v[182:185], v[80:83]
	v_mfma_f32_16x16x32_bf16 v[76:79], v[214:217], v[182:185], v[76:79]
	v_mfma_f32_16x16x32_bf16 v[72:75], v[206:209], v[190:193], v[72:75]
	v_mfma_f32_16x16x32_bf16 v[68:71], v[214:217], v[190:193], v[68:71]
	s_mov_b32 m0, s54
	s_barrier
	ds_read_b128 v[162:165], v144 offset:16384
	ds_read_b128 v[166:169], v144 offset:17408
	ds_read_b128 v[170:173], v144 offset:18432
	ds_read_b128 v[174:177], v144 offset:19456
	ds_read_b128 v[178:181], v144 offset:20480
	ds_read_b128 v[182:185], v144 offset:21504
	ds_read_b128 v[186:189], v144 offset:22528
	global_load_lds_dwordx4 v0, s[52:53]
	s_mov_b32 m0, s55
	ds_read_b128 v[190:193], v144 offset:23552
	global_load_lds_dwordx4 v134, s[52:53]
	s_barrier
	s_waitcnt lgkmcnt(0)
	v_mfma_f32_16x16x32_bf16 v[64:67], v[146:149], v[162:165], 0
	v_mfma_f32_16x16x32_bf16 v[60:63], v[154:157], v[162:165], 0
	v_mfma_f32_16x16x32_bf16 v[56:59], v[146:149], v[170:173], 0
	v_mfma_f32_16x16x32_bf16 v[52:55], v[154:157], v[170:173], 0
	v_mfma_f32_16x16x32_bf16 v[40:43], v[146:149], v[178:181], 0
	v_mfma_f32_16x16x32_bf16 v[36:39], v[154:157], v[178:181], 0
	v_mfma_f32_16x16x32_bf16 v[24:27], v[146:149], v[186:189], 0
	v_mfma_f32_16x16x32_bf16 v[16:19], v[154:157], v[186:189], 0
	v_mfma_f32_16x16x32_bf16 v[64:67], v[150:153], v[166:169], v[64:67]
	v_mfma_f32_16x16x32_bf16 v[60:63], v[158:161], v[166:169], v[60:63]
	v_mfma_f32_16x16x32_bf16 v[56:59], v[150:153], v[174:177], v[56:59]
	v_mfma_f32_16x16x32_bf16 v[52:55], v[158:161], v[174:177], v[52:55]
	v_mfma_f32_16x16x32_bf16 v[40:43], v[150:153], v[182:185], v[40:43]
	v_mfma_f32_16x16x32_bf16 v[36:39], v[158:161], v[182:185], v[36:39]
	v_mfma_f32_16x16x32_bf16 v[24:27], v[150:153], v[190:193], v[24:27]
	v_mfma_f32_16x16x32_bf16 v[16:19], v[158:161], v[190:193], v[16:19]
	s_barrier
	s_add_i32 s23, s23, s37
	s_mov_b32 m0, s23
	s_add_u32 s24, s50, 0x40000
	s_addc_u32 s25, s51, 0
	global_load_lds_dwordx4 v132, s[24:25]
	s_add_i32 m0, s23, 0x2000
	s_waitcnt vmcnt(5)
	global_load_lds_dwordx4 v136, s[24:25]
	s_barrier
	v_mfma_f32_16x16x32_bf16 v[48:51], v[202:205], v[162:165], 0
	v_mfma_f32_16x16x32_bf16 v[44:47], v[210:213], v[162:165], 0
	v_mfma_f32_16x16x32_bf16 v[32:35], v[202:205], v[170:173], 0
	v_mfma_f32_16x16x32_bf16 v[28:31], v[210:213], v[170:173], 0
	v_mfma_f32_16x16x32_bf16 v[20:23], v[202:205], v[178:181], 0
	v_mfma_f32_16x16x32_bf16 v[12:15], v[210:213], v[178:181], 0
	v_mfma_f32_16x16x32_bf16 v[8:11], v[202:205], v[186:189], 0
	v_mfma_f32_16x16x32_bf16 v[4:7], v[210:213], v[186:189], 0
	v_mfma_f32_16x16x32_bf16 v[48:51], v[206:209], v[166:169], v[48:51]
	v_mfma_f32_16x16x32_bf16 v[44:47], v[214:217], v[166:169], v[44:47]
	v_mfma_f32_16x16x32_bf16 v[32:35], v[206:209], v[174:177], v[32:35]
	v_mfma_f32_16x16x32_bf16 v[28:31], v[214:217], v[174:177], v[28:31]
	v_mfma_f32_16x16x32_bf16 v[20:23], v[206:209], v[182:185], v[20:23]
	v_mfma_f32_16x16x32_bf16 v[12:15], v[214:217], v[182:185], v[12:15]
	v_mfma_f32_16x16x32_bf16 v[8:11], v[206:209], v[190:193], v[8:11]
	v_mfma_f32_16x16x32_bf16 v[4:7], v[214:217], v[190:193], v[4:7]
	s_add_i32 s23, 0, 0x18000
	s_barrier
	ds_read_b128 v[146:149], v194 offset:32768
	ds_read_b128 v[150:153], v194 offset:33792
	ds_read_b128 v[154:157], v194 offset:34816
	ds_read_b128 v[158:161], v194 offset:35840
	s_add_u32 s24, s52, 0x40000
	s_addc_u32 s25, s53, 0
	s_mov_b32 m0, s56
	ds_read_b128 v[162:165], v144 offset:32768
	ds_read_b128 v[166:169], v144 offset:33792
	ds_read_b128 v[170:173], v144 offset:34816
	ds_read_b128 v[174:177], v144 offset:35840
	ds_read_b128 v[178:181], v144 offset:36864
	ds_read_b128 v[182:185], v144 offset:37888
	ds_read_b128 v[186:189], v144 offset:38912
	global_load_lds_dwordx4 v0, s[24:25]
	s_mov_b32 m0, s57
	ds_read_b128 v[190:193], v144 offset:39936
	global_load_lds_dwordx4 v134, s[24:25]
	s_waitcnt lgkmcnt(8)
	s_barrier
	s_waitcnt lgkmcnt(0)
	v_mfma_f32_16x16x32_bf16 v[128:131], v[146:149], v[162:165], v[128:131]
	v_mfma_f32_16x16x32_bf16 v[124:127], v[154:157], v[162:165], v[124:127]
	v_mfma_f32_16x16x32_bf16 v[120:123], v[146:149], v[170:173], v[120:123]
	v_mfma_f32_16x16x32_bf16 v[116:119], v[154:157], v[170:173], v[116:119]
	v_mfma_f32_16x16x32_bf16 v[104:107], v[146:149], v[178:181], v[104:107]
	v_mfma_f32_16x16x32_bf16 v[100:103], v[154:157], v[178:181], v[100:103]
	v_mfma_f32_16x16x32_bf16 v[88:91], v[146:149], v[186:189], v[88:91]
	v_mfma_f32_16x16x32_bf16 v[84:87], v[154:157], v[186:189], v[84:87]
	v_mfma_f32_16x16x32_bf16 v[128:131], v[150:153], v[166:169], v[128:131]
	v_mfma_f32_16x16x32_bf16 v[124:127], v[158:161], v[166:169], v[124:127]
	v_mfma_f32_16x16x32_bf16 v[120:123], v[150:153], v[174:177], v[120:123]
	v_mfma_f32_16x16x32_bf16 v[116:119], v[158:161], v[174:177], v[116:119]
	v_mfma_f32_16x16x32_bf16 v[104:107], v[150:153], v[182:185], v[104:107]
	v_mfma_f32_16x16x32_bf16 v[100:103], v[158:161], v[182:185], v[100:103]
	v_mfma_f32_16x16x32_bf16 v[88:91], v[150:153], v[190:193], v[88:91]
	v_mfma_f32_16x16x32_bf16 v[84:87], v[158:161], v[190:193], v[84:87]
	s_barrier
	s_add_i32 s26, 0, 0x1c000
	s_add_i32 s23, s23, s37
	s_mov_b32 m0, s23
	ds_read_b128 v[202:205], v194 offset:49152
	ds_read_b128 v[206:209], v194 offset:50176
	ds_read_b128 v[210:213], v194 offset:51200
	s_add_u32 s98, s50, 0x80
	s_addc_u32 s99, s51, 0
	global_load_lds_dwordx4 v132, s[98:99]
	s_add_i32 m0, s23, 0x2000
	ds_read_b128 v[214:217], v194 offset:52224
	global_load_lds_dwordx4 v136, s[98:99]
	s_barrier
	s_waitcnt lgkmcnt(0)
	v_mfma_f32_16x16x32_bf16 v[112:115], v[202:205], v[162:165], v[112:115]
	v_mfma_f32_16x16x32_bf16 v[108:111], v[210:213], v[162:165], v[108:111]
	v_mfma_f32_16x16x32_bf16 v[96:99], v[202:205], v[170:173], v[96:99]
	v_mfma_f32_16x16x32_bf16 v[92:95], v[210:213], v[170:173], v[92:95]
	v_mfma_f32_16x16x32_bf16 v[80:83], v[202:205], v[178:181], v[80:83]
	v_mfma_f32_16x16x32_bf16 v[76:79], v[210:213], v[178:181], v[76:79]
	v_mfma_f32_16x16x32_bf16 v[72:75], v[202:205], v[186:189], v[72:75]
	v_mfma_f32_16x16x32_bf16 v[68:71], v[210:213], v[186:189], v[68:71]
	v_mfma_f32_16x16x32_bf16 v[112:115], v[206:209], v[166:169], v[112:115]
	v_mfma_f32_16x16x32_bf16 v[108:111], v[214:217], v[166:169], v[108:111]
	v_mfma_f32_16x16x32_bf16 v[96:99], v[206:209], v[174:177], v[96:99]
	v_mfma_f32_16x16x32_bf16 v[92:95], v[214:217], v[174:177], v[92:95]
	v_mfma_f32_16x16x32_bf16 v[80:83], v[206:209], v[182:185], v[80:83]
	v_mfma_f32_16x16x32_bf16 v[76:79], v[214:217], v[182:185], v[76:79]
	v_mfma_f32_16x16x32_bf16 v[72:75], v[206:209], v[190:193], v[72:75]
	v_mfma_f32_16x16x32_bf16 v[68:71], v[214:217], v[190:193], v[68:71]
	s_mov_b32 m0, s59
	s_barrier
	ds_read_b128 v[162:165], v144 offset:49152
	ds_read_b128 v[166:169], v144 offset:50176
	ds_read_b128 v[170:173], v144 offset:51200
	ds_read_b128 v[174:177], v144 offset:52224
	ds_read_b128 v[178:181], v144 offset:53248
	ds_read_b128 v[182:185], v144 offset:54272
	ds_read_b128 v[186:189], v144 offset:55296
	s_add_u32 s98, s52, 0x80
	s_addc_u32 s99, s53, 0
	global_load_lds_dwordx4 v0, s[98:99]
	s_mov_b32 m0, s60
	ds_read_b128 v[190:193], v144 offset:56320
	global_load_lds_dwordx4 v134, s[98:99]
	s_barrier
	s_waitcnt lgkmcnt(0)
	v_mfma_f32_16x16x32_bf16 v[64:67], v[146:149], v[162:165], v[64:67]
	v_mfma_f32_16x16x32_bf16 v[60:63], v[154:157], v[162:165], v[60:63]
	v_mfma_f32_16x16x32_bf16 v[56:59], v[146:149], v[170:173], v[56:59]
	v_mfma_f32_16x16x32_bf16 v[52:55], v[154:157], v[170:173], v[52:55]
	v_mfma_f32_16x16x32_bf16 v[40:43], v[146:149], v[178:181], v[40:43]
	v_mfma_f32_16x16x32_bf16 v[36:39], v[154:157], v[178:181], v[36:39]
	v_mfma_f32_16x16x32_bf16 v[24:27], v[146:149], v[186:189], v[24:27]
	v_mfma_f32_16x16x32_bf16 v[16:19], v[154:157], v[186:189], v[16:19]
	v_mfma_f32_16x16x32_bf16 v[64:67], v[150:153], v[166:169], v[64:67]
	v_mfma_f32_16x16x32_bf16 v[60:63], v[158:161], v[166:169], v[60:63]
	v_mfma_f32_16x16x32_bf16 v[56:59], v[150:153], v[174:177], v[56:59]
	v_mfma_f32_16x16x32_bf16 v[52:55], v[158:161], v[174:177], v[52:55]
	v_mfma_f32_16x16x32_bf16 v[40:43], v[150:153], v[182:185], v[40:43]
	v_mfma_f32_16x16x32_bf16 v[36:39], v[158:161], v[182:185], v[36:39]
	v_mfma_f32_16x16x32_bf16 v[24:27], v[150:153], v[190:193], v[24:27]
	v_mfma_f32_16x16x32_bf16 v[16:19], v[158:161], v[190:193], v[16:19]
	s_barrier
	s_add_i32 s23, s26, s37
	s_mov_b32 m0, s23
	s_add_u32 s24, s50, 0x40080
	s_addc_u32 s25, s51, 0
	global_load_lds_dwordx4 v132, s[24:25]
	s_add_i32 m0, s23, 0x2000
	s_waitcnt vmcnt(5)
	global_load_lds_dwordx4 v136, s[24:25]
	s_barrier
	v_mfma_f32_16x16x32_bf16 v[48:51], v[202:205], v[162:165], v[48:51]
	v_mfma_f32_16x16x32_bf16 v[44:47], v[210:213], v[162:165], v[44:47]
	v_mfma_f32_16x16x32_bf16 v[32:35], v[202:205], v[170:173], v[32:35]
	v_mfma_f32_16x16x32_bf16 v[28:31], v[210:213], v[170:173], v[28:31]
	v_mfma_f32_16x16x32_bf16 v[20:23], v[202:205], v[178:181], v[20:23]
	v_mfma_f32_16x16x32_bf16 v[12:15], v[210:213], v[178:181], v[12:15]
	v_mfma_f32_16x16x32_bf16 v[8:11], v[202:205], v[186:189], v[8:11]
	v_mfma_f32_16x16x32_bf16 v[4:7], v[210:213], v[186:189], v[4:7]
	v_mfma_f32_16x16x32_bf16 v[48:51], v[206:209], v[166:169], v[48:51]
	v_mfma_f32_16x16x32_bf16 v[44:47], v[214:217], v[166:169], v[44:47]
	v_mfma_f32_16x16x32_bf16 v[32:35], v[206:209], v[174:177], v[32:35]
	v_mfma_f32_16x16x32_bf16 v[28:31], v[214:217], v[174:177], v[28:31]
	v_mfma_f32_16x16x32_bf16 v[20:23], v[206:209], v[182:185], v[20:23]
	v_mfma_f32_16x16x32_bf16 v[12:15], v[214:217], v[182:185], v[12:15]
	v_mfma_f32_16x16x32_bf16 v[8:11], v[206:209], v[190:193], v[8:11]
	v_mfma_f32_16x16x32_bf16 v[4:7], v[214:217], v[190:193], v[4:7]
	s_add_i32 s22, s22, 2
	s_add_u32 s48, s48, 0x100
	s_addc_u32 s49, s49, 0
	s_add_u32 s20, s20, 0x100
	s_addc_u32 s21, s21, 0
	s_cmp_gt_u32 s22, 13
	s_barrier
	s_cbranch_scc1 .Lpeel_out_136

.Lpeel_out_136:
	v_lshl_add_u32 v146, s0, 8, v142
	v_cvt_pk_bf16_f32 v72, v72, v73
	v_cvt_pk_bf16_f32 v73, v74, v75
	v_cvt_pk_bf16_f32 v74, v68, v69
	v_add_u32_e32 v68, 0x80, v146
	s_lshl_b32 s0, s1, 8
	v_ashrrev_i32_e32 v147, 31, v146
	v_readlane_b32 s20, v252, 12
	v_cvt_pk_bf16_f32 v112, v112, v113
	v_cvt_pk_bf16_f32 v113, v114, v115
	v_cvt_pk_bf16_f32 v114, v108, v109
	v_or_b32_e32 v108, 16, v146
	v_ashrrev_i32_e32 v69, 31, v68
	v_cvt_pk_bf16_f32 v48, v48, v49
	v_cvt_pk_bf16_f32 v49, v50, v51
	v_cvt_pk_bf16_f32 v50, v44, v45
	v_add_u32_e32 v44, 0x90, v146
	s_ashr_i32 s1, s0, 31
	v_lshlrev_b64 v[148:149], 11, v[146:147]
	v_readlane_b32 s21, v252, 13
	v_ashrrev_i32_e32 v109, 31, v108
	v_cvt_pk_bf16_f32 v96, v96, v97
	v_cvt_pk_bf16_f32 v97, v98, v99
	v_cvt_pk_bf16_f32 v98, v92, v93
	v_or_b32_e32 v92, 32, v146
	v_lshlrev_b64 v[68:69], 11, v[68:69]
	v_ashrrev_i32_e32 v45, 31, v44
	v_cvt_pk_bf16_f32 v32, v32, v33
	v_cvt_pk_bf16_f32 v33, v34, v35
	v_cvt_pk_bf16_f32 v34, v28, v29
	v_add_u32_e32 v28, 0xa0, v146
	v_lshl_add_u64 v[148:149], s[20:21], 0, v[148:149]
	s_lshl_b64 s[0:1], s[0:1], 1
	v_lshlrev_b64 v[108:109], 11, v[108:109]
	v_ashrrev_i32_e32 v93, 31, v92
	v_cvt_pk_bf16_f32 v80, v80, v81
	v_cvt_pk_bf16_f32 v81, v82, v83
	v_cvt_pk_bf16_f32 v82, v76, v77
	v_or_b32_e32 v76, 48, v146
	v_lshl_add_u64 v[68:69], s[20:21], 0, v[68:69]
	v_lshlrev_b64 v[44:45], 11, v[44:45]
	v_ashrrev_i32_e32 v29, 31, v28
	v_cvt_pk_bf16_f32 v20, v20, v21
	v_cvt_pk_bf16_f32 v21, v22, v23
	v_cvt_pk_bf16_f32 v22, v12, v13
	v_add_u32_e32 v12, 0xb0, v146
	v_lshl_add_u64 v[148:149], v[148:149], 0, s[0:1]
	v_lshl_add_u64 v[108:109], s[20:21], 0, v[108:109]
	v_lshlrev_b64 v[92:93], 11, v[92:93]
	v_ashrrev_i32_e32 v77, 31, v76
	v_lshl_add_u64 v[68:69], v[68:69], 0, s[0:1]
	v_lshl_add_u64 v[44:45], s[20:21], 0, v[44:45]
	v_lshlrev_b64 v[28:29], 11, v[28:29]
	v_ashrrev_i32_e32 v13, 31, v12
	v_lshl_add_u64 v[148:149], v[148:149], 0, s[72:73]
	v_lshl_add_u64 v[108:109], v[108:109], 0, s[0:1]
	v_lshl_add_u64 v[92:93], s[20:21], 0, v[92:93]
	v_lshlrev_b64 v[76:77], 11, v[76:77]
	v_lshl_add_u64 v[68:69], v[68:69], 0, s[72:73]
	v_lshl_add_u64 v[44:45], v[44:45], 0, s[0:1]
	v_lshl_add_u64 v[28:29], s[20:21], 0, v[28:29]
	v_lshlrev_b64 v[12:13], 11, v[12:13]
	v_lshl_add_u64 v[148:149], v[148:149], 0, v[2:3]
	v_cvt_pk_bf16_f32 v115, v110, v111
	v_lshl_add_u64 v[108:109], v[108:109], 0, s[72:73]
	v_lshl_add_u64 v[92:93], v[92:93], 0, s[0:1]
	v_lshl_add_u64 v[76:77], s[20:21], 0, v[76:77]
	v_lshl_add_u64 v[68:69], v[68:69], 0, v[2:3]
	v_cvt_pk_bf16_f32 v51, v46, v47
	v_lshl_add_u64 v[44:45], v[44:45], 0, s[72:73]
	v_lshl_add_u64 v[28:29], v[28:29], 0, s[0:1]
	v_lshl_add_u64 v[12:13], s[20:21], 0, v[12:13]
	global_store_dwordx4 v[148:149], v[112:115], off offset:256
	v_cvt_pk_bf16_f32 v99, v94, v95
	v_lshl_add_u64 v[92:93], v[92:93], 0, s[72:73]
	v_lshl_add_u64 v[112:113], v[108:109], 0, v[2:3]
	v_lshl_add_u64 v[76:77], v[76:77], 0, s[0:1]
	global_store_dwordx4 v[68:69], v[48:51], off offset:256
	v_cvt_pk_bf16_f32 v35, v30, v31
	v_lshl_add_u64 v[28:29], v[28:29], 0, s[72:73]
	v_lshl_add_u64 v[48:49], v[44:45], 0, v[2:3]
	v_lshl_add_u64 v[12:13], v[12:13], 0, s[0:1]
	global_store_dwordx4 v[112:113], v[96:99], off offset:256
	v_cvt_pk_bf16_f32 v83, v78, v79
	v_lshl_add_u64 v[76:77], v[76:77], 0, s[72:73]
	v_lshl_add_u64 v[96:97], v[92:93], 0, v[2:3]
	global_store_dwordx4 v[48:49], v[32:35], off offset:256
	v_cvt_pk_bf16_f32 v23, v14, v15
	v_lshl_add_u64 v[12:13], v[12:13], 0, s[72:73]
	v_lshl_add_u64 v[32:33], v[28:29], 0, v[2:3]
	v_cvt_pk_bf16_f32 v128, v128, v129
	v_cvt_pk_bf16_f32 v129, v130, v131
	v_cvt_pk_bf16_f32 v130, v124, v125
	v_cvt_pk_bf16_f32 v131, v126, v127
	v_cvt_pk_bf16_f32 v108, v120, v121
	v_cvt_pk_bf16_f32 v109, v122, v123
	v_cvt_pk_bf16_f32 v110, v116, v117
	v_cvt_pk_bf16_f32 v111, v118, v119
	v_cvt_pk_bf16_f32 v92, v104, v105
	v_cvt_pk_bf16_f32 v93, v106, v107
	v_cvt_pk_bf16_f32 v94, v100, v101
	v_cvt_pk_bf16_f32 v95, v102, v103
	global_store_dwordx4 v[96:97], v[80:83], off offset:256
	v_cvt_pk_bf16_f32 v78, v84, v85
	v_cvt_pk_bf16_f32 v79, v86, v87
	v_lshl_add_u64 v[80:81], v[76:77], 0, v[2:3]
	v_cvt_pk_bf16_f32 v76, v88, v89
	v_cvt_pk_bf16_f32 v77, v90, v91
	v_cvt_pk_bf16_f32 v75, v70, v71
	v_cvt_pk_bf16_f32 v64, v64, v65
	v_cvt_pk_bf16_f32 v65, v66, v67
	v_cvt_pk_bf16_f32 v66, v60, v61
	v_cvt_pk_bf16_f32 v67, v62, v63
	v_cvt_pk_bf16_f32 v44, v56, v57
	v_cvt_pk_bf16_f32 v45, v58, v59
	v_cvt_pk_bf16_f32 v46, v52, v53
	v_cvt_pk_bf16_f32 v47, v54, v55
	v_cvt_pk_bf16_f32 v28, v40, v41
	v_cvt_pk_bf16_f32 v29, v42, v43
	v_cvt_pk_bf16_f32 v30, v36, v37
	v_cvt_pk_bf16_f32 v31, v38, v39
	global_store_dwordx4 v[32:33], v[20:23], off offset:256
	v_cvt_pk_bf16_f32 v14, v16, v17
	v_cvt_pk_bf16_f32 v15, v18, v19
	v_lshl_add_u64 v[20:21], v[12:13], 0, v[2:3]
	v_cvt_pk_bf16_f32 v12, v24, v25
	v_cvt_pk_bf16_f32 v13, v26, v27
	v_cvt_pk_bf16_f32 v8, v8, v9
	v_cvt_pk_bf16_f32 v9, v10, v11
	v_cvt_pk_bf16_f32 v10, v4, v5
	v_cvt_pk_bf16_f32 v11, v6, v7
	s_and_b64 vcc, exec, s[38:39]
	s_mov_b32 s1, s40
	s_mov_b32 s0, s42
	s_mov_b64 s[50:51], s[46:47]
	s_mov_b64 s[48:49], s[44:45]
	global_store_dwordx4 v[148:149], v[128:131], off
	global_store_dwordx4 v[112:113], v[108:111], off
	global_store_dwordx4 v[96:97], v[92:95], off
	global_store_dwordx4 v[80:81], v[76:79], off
	global_store_dwordx4 v[80:81], v[72:75], off offset:256
	global_store_dwordx4 v[68:69], v[64:67], off
	global_store_dwordx4 v[48:49], v[44:47], off
	global_store_dwordx4 v[32:33], v[28:31], off
	global_store_dwordx4 v[20:21], v[12:15], off
	global_store_dwordx4 v[20:21], v[8:11], off offset:256
	s_cbranch_vccz .LBB0_129
	s_waitcnt vmcnt(0)
	s_cmpk_gt_u32 s31, 0xff
	s_cbranch_scc1 .LBB0_140
	s_barrier

.LBB0_241:
	s_add_u32 s0, s0, 0x40080
	s_addc_u32 s1, s1, 0
	s_add_u32 s20, s44, 0x100
	s_addc_u32 s21, s45, 0
	s_mov_b32 s22, -2
	v_add_u32_e32 v216, 0x10000, v187
	s_add_u32 s23, s0, 0xfffc0080
	s_addc_u32 s24, s1, -1
	s_add_i32 s25, 0, 0x10000
	ds_read_b128 v[132:135], v216
	ds_read_b128 v[136:139], v216 offset:1024
	ds_read_b128 v[140:143], v216 offset:2048
	ds_read_b128 v[144:147], v216 offset:3072
	s_cmp_eq_u32 s22, 12
	s_cselect_b32 s47, s57, s24
	s_cselect_b32 s46, s56, s23
	s_cselect_b32 s45, s59, s21
	s_cselect_b32 s44, s58, s20
	s_add_i32 m0, s67, 0xc000
	ds_read_b128 v[148:151], v240
	ds_read_b128 v[152:155], v240 offset:1024
	ds_read_b128 v[156:159], v240 offset:2048
	ds_read_b128 v[160:163], v240 offset:3072
	ds_read_b128 v[164:167], v240 offset:4096
	ds_read_b128 v[168:171], v240 offset:5120
	ds_read_b128 v[172:175], v240 offset:6144
	global_load_lds_dwordx4 v194, s[0:1]
	s_add_i32 m0, s67, 0xe000
	ds_read_b128 v[204:207], v240 offset:7168
	global_load_lds_dwordx4 v202, s[0:1]
	s_waitcnt lgkmcnt(8)
	s_barrier
	s_waitcnt lgkmcnt(0)
	v_mfma_f32_16x16x32_bf16 v[128:131], v[132:135], v[148:151], 0
	v_mfma_f32_16x16x32_bf16 v[124:127], v[140:143], v[148:151], 0
	v_mfma_f32_16x16x32_bf16 v[120:123], v[132:135], v[156:159], 0
	v_mfma_f32_16x16x32_bf16 v[116:119], v[140:143], v[156:159], 0
	v_mfma_f32_16x16x32_bf16 v[112:115], v[132:135], v[164:167], 0
	v_mfma_f32_16x16x32_bf16 v[108:111], v[140:143], v[164:167], 0
	v_mfma_f32_16x16x32_bf16 v[104:107], v[132:135], v[172:175], 0
	v_mfma_f32_16x16x32_bf16 v[100:103], v[140:143], v[172:175], 0
	v_mfma_f32_16x16x32_bf16 v[128:131], v[136:139], v[152:155], v[128:131]
	v_mfma_f32_16x16x32_bf16 v[124:127], v[144:147], v[152:155], v[124:127]
	v_mfma_f32_16x16x32_bf16 v[120:123], v[136:139], v[160:163], v[120:123]
	v_mfma_f32_16x16x32_bf16 v[116:119], v[144:147], v[160:163], v[116:119]
	v_mfma_f32_16x16x32_bf16 v[112:115], v[136:139], v[168:171], v[112:115]
	v_mfma_f32_16x16x32_bf16 v[108:111], v[144:147], v[168:171], v[108:111]
	v_mfma_f32_16x16x32_bf16 v[104:107], v[136:139], v[204:207], v[104:107]
	v_mfma_f32_16x16x32_bf16 v[100:103], v[144:147], v[204:207], v[100:103]
	s_barrier
	s_add_i32 s23, 0, 0x14000
	s_add_i32 s24, s25, s61
	s_mov_b32 m0, s24
	ds_read_b128 v[208:211], v216 offset:16384
	ds_read_b128 v[212:215], v216 offset:17408
	ds_read_b128 v[242:245], v216 offset:18432
	global_load_lds_dwordx4 v176, s[44:45]
	s_add_i32 m0, s24, 0x2000
	ds_read_b128 v[246:249], v216 offset:19456
	global_load_lds_dwordx4 v180, s[44:45]
	s_barrier
	s_waitcnt lgkmcnt(0)
	v_mfma_f32_16x16x32_bf16 v[64:67], v[208:211], v[148:151], 0
	v_mfma_f32_16x16x32_bf16 v[60:63], v[242:245], v[148:151], 0
	v_mfma_f32_16x16x32_bf16 v[56:59], v[208:211], v[156:159], 0
	v_mfma_f32_16x16x32_bf16 v[52:55], v[242:245], v[156:159], 0
	v_mfma_f32_16x16x32_bf16 v[48:51], v[208:211], v[164:167], 0
	v_mfma_f32_16x16x32_bf16 v[44:47], v[242:245], v[164:167], 0
	v_mfma_f32_16x16x32_bf16 v[40:43], v[208:211], v[172:175], 0
	v_mfma_f32_16x16x32_bf16 v[36:39], v[242:245], v[172:175], 0
	v_mfma_f32_16x16x32_bf16 v[64:67], v[212:215], v[152:155], v[64:67]
	v_mfma_f32_16x16x32_bf16 v[60:63], v[246:249], v[152:155], v[60:63]
	v_mfma_f32_16x16x32_bf16 v[56:59], v[212:215], v[160:163], v[56:59]
	v_mfma_f32_16x16x32_bf16 v[52:55], v[246:249], v[160:163], v[52:55]
	v_mfma_f32_16x16x32_bf16 v[48:51], v[212:215], v[168:171], v[48:51]
	v_mfma_f32_16x16x32_bf16 v[44:47], v[246:249], v[168:171], v[44:47]
	v_mfma_f32_16x16x32_bf16 v[40:43], v[212:215], v[204:207], v[40:43]
	v_mfma_f32_16x16x32_bf16 v[36:39], v[246:249], v[204:207], v[36:39]
	s_mov_b32 m0, s67
	s_barrier
	ds_read_b128 v[148:151], v240 offset:16384
	ds_read_b128 v[152:155], v240 offset:17408
	ds_read_b128 v[156:159], v240 offset:18432
	ds_read_b128 v[160:163], v240 offset:19456
	ds_read_b128 v[164:167], v240 offset:20480
	ds_read_b128 v[168:171], v240 offset:21504
	ds_read_b128 v[172:175], v240 offset:22528
	global_load_lds_dwordx4 v0, s[46:47]
	s_mov_b32 m0, s74
	ds_read_b128 v[204:207], v240 offset:23552
	global_load_lds_dwordx4 v178, s[46:47]
	s_barrier
	s_waitcnt lgkmcnt(0)
	v_mfma_f32_16x16x32_bf16 v[96:99], v[132:135], v[148:151], 0
	v_mfma_f32_16x16x32_bf16 v[92:95], v[140:143], v[148:151], 0
	v_mfma_f32_16x16x32_bf16 v[88:91], v[132:135], v[156:159], 0
	v_mfma_f32_16x16x32_bf16 v[84:87], v[140:143], v[156:159], 0
	v_mfma_f32_16x16x32_bf16 v[80:83], v[132:135], v[164:167], 0
	v_mfma_f32_16x16x32_bf16 v[76:79], v[140:143], v[164:167], 0
	v_mfma_f32_16x16x32_bf16 v[72:75], v[132:135], v[172:175], 0
	v_mfma_f32_16x16x32_bf16 v[68:71], v[140:143], v[172:175], 0
	v_mfma_f32_16x16x32_bf16 v[96:99], v[136:139], v[152:155], v[96:99]
	v_mfma_f32_16x16x32_bf16 v[92:95], v[144:147], v[152:155], v[92:95]
	v_mfma_f32_16x16x32_bf16 v[88:91], v[136:139], v[160:163], v[88:91]
	v_mfma_f32_16x16x32_bf16 v[84:87], v[144:147], v[160:163], v[84:87]
	v_mfma_f32_16x16x32_bf16 v[80:83], v[136:139], v[168:171], v[80:83]
	v_mfma_f32_16x16x32_bf16 v[76:79], v[144:147], v[168:171], v[76:79]
	v_mfma_f32_16x16x32_bf16 v[72:75], v[136:139], v[204:207], v[72:75]
	v_mfma_f32_16x16x32_bf16 v[68:71], v[144:147], v[204:207], v[68:71]
	s_barrier
	s_add_i32 s23, s23, s61
	s_mov_b32 m0, s23
	s_add_u32 s24, s44, 0x40000
	s_addc_u32 s25, s45, 0
	global_load_lds_dwordx4 v176, s[24:25]
	s_add_i32 m0, s23, 0x2000
	s_waitcnt vmcnt(5)
	global_load_lds_dwordx4 v180, s[24:25]
	s_barrier
	v_mfma_f32_16x16x32_bf16 v[32:35], v[208:211], v[148:151], 0
	v_mfma_f32_16x16x32_bf16 v[28:31], v[242:245], v[148:151], 0
	v_mfma_f32_16x16x32_bf16 v[24:27], v[208:211], v[156:159], 0
	v_mfma_f32_16x16x32_bf16 v[20:23], v[242:245], v[156:159], 0
	v_mfma_f32_16x16x32_bf16 v[16:19], v[208:211], v[164:167], 0
	v_mfma_f32_16x16x32_bf16 v[12:15], v[242:245], v[164:167], 0
	v_mfma_f32_16x16x32_bf16 v[8:11], v[208:211], v[172:175], 0
	v_mfma_f32_16x16x32_bf16 v[4:7], v[242:245], v[172:175], 0
	v_mfma_f32_16x16x32_bf16 v[32:35], v[212:215], v[152:155], v[32:35]
	v_mfma_f32_16x16x32_bf16 v[28:31], v[246:249], v[152:155], v[28:31]
	v_mfma_f32_16x16x32_bf16 v[24:27], v[212:215], v[160:163], v[24:27]
	v_mfma_f32_16x16x32_bf16 v[20:23], v[246:249], v[160:163], v[20:23]
	v_mfma_f32_16x16x32_bf16 v[16:19], v[212:215], v[168:171], v[16:19]
	v_mfma_f32_16x16x32_bf16 v[12:15], v[246:249], v[168:171], v[12:15]
	v_mfma_f32_16x16x32_bf16 v[8:11], v[212:215], v[204:207], v[8:11]
	v_mfma_f32_16x16x32_bf16 v[4:7], v[246:249], v[204:207], v[4:7]
	s_add_i32 s23, 0, 0x18000
	s_barrier
	ds_read_b128 v[132:135], v216 offset:32768
	ds_read_b128 v[136:139], v216 offset:33792
	ds_read_b128 v[140:143], v216 offset:34816
	ds_read_b128 v[144:147], v216 offset:35840
	s_add_u32 s24, s46, 0x40000
	s_addc_u32 s25, s47, 0
	s_mov_b32 m0, s75
	ds_read_b128 v[148:151], v240 offset:32768
	ds_read_b128 v[152:155], v240 offset:33792
	ds_read_b128 v[156:159], v240 offset:34816
	ds_read_b128 v[160:163], v240 offset:35840
	ds_read_b128 v[164:167], v240 offset:36864
	ds_read_b128 v[168:171], v240 offset:37888
	ds_read_b128 v[172:175], v240 offset:38912
	global_load_lds_dwordx4 v0, s[24:25]
	s_mov_b32 m0, s82
	ds_read_b128 v[204:207], v240 offset:39936
	global_load_lds_dwordx4 v178, s[24:25]
	s_waitcnt lgkmcnt(8)
	s_barrier
	s_waitcnt lgkmcnt(0)
	v_mfma_f32_16x16x32_bf16 v[128:131], v[132:135], v[148:151], v[128:131]
	v_mfma_f32_16x16x32_bf16 v[124:127], v[140:143], v[148:151], v[124:127]
	v_mfma_f32_16x16x32_bf16 v[120:123], v[132:135], v[156:159], v[120:123]
	v_mfma_f32_16x16x32_bf16 v[116:119], v[140:143], v[156:159], v[116:119]
	v_mfma_f32_16x16x32_bf16 v[112:115], v[132:135], v[164:167], v[112:115]
	v_mfma_f32_16x16x32_bf16 v[108:111], v[140:143], v[164:167], v[108:111]
	v_mfma_f32_16x16x32_bf16 v[104:107], v[132:135], v[172:175], v[104:107]
	v_mfma_f32_16x16x32_bf16 v[100:103], v[140:143], v[172:175], v[100:103]
	v_mfma_f32_16x16x32_bf16 v[128:131], v[136:139], v[152:155], v[128:131]
	v_mfma_f32_16x16x32_bf16 v[124:127], v[144:147], v[152:155], v[124:127]
	v_mfma_f32_16x16x32_bf16 v[120:123], v[136:139], v[160:163], v[120:123]
	v_mfma_f32_16x16x32_bf16 v[116:119], v[144:147], v[160:163], v[116:119]
	v_mfma_f32_16x16x32_bf16 v[112:115], v[136:139], v[168:171], v[112:115]
	v_mfma_f32_16x16x32_bf16 v[108:111], v[144:147], v[168:171], v[108:111]
	v_mfma_f32_16x16x32_bf16 v[104:107], v[136:139], v[204:207], v[104:107]
	v_mfma_f32_16x16x32_bf16 v[100:103], v[144:147], v[204:207], v[100:103]
	s_barrier
	s_add_i32 s26, 0, 0x1c000
	s_add_i32 s23, s23, s61
	s_mov_b32 m0, s23
	ds_read_b128 v[208:211], v216 offset:49152
	ds_read_b128 v[212:215], v216 offset:50176
	ds_read_b128 v[242:245], v216 offset:51200
	s_add_u32 s98, s44, 0x80
	s_addc_u32 s99, s45, 0
	global_load_lds_dwordx4 v176, s[98:99]
	s_add_i32 m0, s23, 0x2000
	ds_read_b128 v[246:249], v216 offset:52224
	global_load_lds_dwordx4 v180, s[98:99]
	s_barrier
	s_waitcnt lgkmcnt(0)
	v_mfma_f32_16x16x32_bf16 v[64:67], v[208:211], v[148:151], v[64:67]
	v_mfma_f32_16x16x32_bf16 v[60:63], v[242:245], v[148:151], v[60:63]
	v_mfma_f32_16x16x32_bf16 v[56:59], v[208:211], v[156:159], v[56:59]
	v_mfma_f32_16x16x32_bf16 v[52:55], v[242:245], v[156:159], v[52:55]
	v_mfma_f32_16x16x32_bf16 v[48:51], v[208:211], v[164:167], v[48:51]
	v_mfma_f32_16x16x32_bf16 v[44:47], v[242:245], v[164:167], v[44:47]
	v_mfma_f32_16x16x32_bf16 v[40:43], v[208:211], v[172:175], v[40:43]
	v_mfma_f32_16x16x32_bf16 v[36:39], v[242:245], v[172:175], v[36:39]
	v_mfma_f32_16x16x32_bf16 v[64:67], v[212:215], v[152:155], v[64:67]
	v_mfma_f32_16x16x32_bf16 v[60:63], v[246:249], v[152:155], v[60:63]
	v_mfma_f32_16x16x32_bf16 v[56:59], v[212:215], v[160:163], v[56:59]
	v_mfma_f32_16x16x32_bf16 v[52:55], v[246:249], v[160:163], v[52:55]
	v_mfma_f32_16x16x32_bf16 v[48:51], v[212:215], v[168:171], v[48:51]
	v_mfma_f32_16x16x32_bf16 v[44:47], v[246:249], v[168:171], v[44:47]
	v_mfma_f32_16x16x32_bf16 v[40:43], v[212:215], v[204:207], v[40:43]
	v_mfma_f32_16x16x32_bf16 v[36:39], v[246:249], v[204:207], v[36:39]
	s_mov_b32 m0, s48
	s_barrier
	ds_read_b128 v[148:151], v240 offset:49152
	ds_read_b128 v[152:155], v240 offset:50176
	ds_read_b128 v[156:159], v240 offset:51200
	ds_read_b128 v[160:163], v240 offset:52224
	ds_read_b128 v[164:167], v240 offset:53248
	ds_read_b128 v[168:171], v240 offset:54272
	ds_read_b128 v[172:175], v240 offset:55296
	s_add_u32 s98, s46, 0x80
	s_addc_u32 s99, s47, 0
	global_load_lds_dwordx4 v0, s[98:99]
	s_mov_b32 m0, s50
	ds_read_b128 v[204:207], v240 offset:56320
	global_load_lds_dwordx4 v178, s[98:99]
	s_barrier
	s_waitcnt lgkmcnt(0)
	v_mfma_f32_16x16x32_bf16 v[96:99], v[132:135], v[148:151], v[96:99]
	v_mfma_f32_16x16x32_bf16 v[92:95], v[140:143], v[148:151], v[92:95]
	v_mfma_f32_16x16x32_bf16 v[88:91], v[132:135], v[156:159], v[88:91]
	v_mfma_f32_16x16x32_bf16 v[84:87], v[140:143], v[156:159], v[84:87]
	v_mfma_f32_16x16x32_bf16 v[80:83], v[132:135], v[164:167], v[80:83]
	v_mfma_f32_16x16x32_bf16 v[76:79], v[140:143], v[164:167], v[76:79]
	v_mfma_f32_16x16x32_bf16 v[72:75], v[132:135], v[172:175], v[72:75]
	v_mfma_f32_16x16x32_bf16 v[68:71], v[140:143], v[172:175], v[68:71]
	v_mfma_f32_16x16x32_bf16 v[96:99], v[136:139], v[152:155], v[96:99]
	v_mfma_f32_16x16x32_bf16 v[92:95], v[144:147], v[152:155], v[92:95]
	v_mfma_f32_16x16x32_bf16 v[88:91], v[136:139], v[160:163], v[88:91]
	v_mfma_f32_16x16x32_bf16 v[84:87], v[144:147], v[160:163], v[84:87]
	v_mfma_f32_16x16x32_bf16 v[80:83], v[136:139], v[168:171], v[80:83]
	v_mfma_f32_16x16x32_bf16 v[76:79], v[144:147], v[168:171], v[76:79]
	v_mfma_f32_16x16x32_bf16 v[72:75], v[136:139], v[204:207], v[72:75]
	v_mfma_f32_16x16x32_bf16 v[68:71], v[144:147], v[204:207], v[68:71]
	s_barrier
	s_add_i32 s23, s26, s61
	s_mov_b32 m0, s23
	s_add_u32 s24, s44, 0x40080
	s_addc_u32 s25, s45, 0
	global_load_lds_dwordx4 v176, s[24:25]
	s_add_i32 m0, s23, 0x2000
	s_waitcnt vmcnt(5)
	global_load_lds_dwordx4 v180, s[24:25]
	s_barrier
	v_mfma_f32_16x16x32_bf16 v[32:35], v[208:211], v[148:151], v[32:35]
	v_mfma_f32_16x16x32_bf16 v[28:31], v[242:245], v[148:151], v[28:31]
	v_mfma_f32_16x16x32_bf16 v[24:27], v[208:211], v[156:159], v[24:27]
	v_mfma_f32_16x16x32_bf16 v[20:23], v[242:245], v[156:159], v[20:23]
	v_mfma_f32_16x16x32_bf16 v[16:19], v[208:211], v[164:167], v[16:19]
	v_mfma_f32_16x16x32_bf16 v[12:15], v[242:245], v[164:167], v[12:15]
	v_mfma_f32_16x16x32_bf16 v[8:11], v[208:211], v[172:175], v[8:11]
	v_mfma_f32_16x16x32_bf16 v[4:7], v[242:245], v[172:175], v[4:7]
	v_mfma_f32_16x16x32_bf16 v[32:35], v[212:215], v[152:155], v[32:35]
	v_mfma_f32_16x16x32_bf16 v[28:31], v[246:249], v[152:155], v[28:31]
	v_mfma_f32_16x16x32_bf16 v[24:27], v[212:215], v[160:163], v[24:27]
	v_mfma_f32_16x16x32_bf16 v[20:23], v[246:249], v[160:163], v[20:23]
	v_mfma_f32_16x16x32_bf16 v[16:19], v[212:215], v[168:171], v[16:19]
	v_mfma_f32_16x16x32_bf16 v[12:15], v[246:249], v[168:171], v[12:15]
	v_mfma_f32_16x16x32_bf16 v[8:11], v[212:215], v[204:207], v[8:11]
	v_mfma_f32_16x16x32_bf16 v[4:7], v[246:249], v[204:207], v[4:7]
	s_add_i32 s22, s22, 2
	s_add_u32 s0, s0, 0x100
	s_addc_u32 s1, s1, 0
	s_add_u32 s20, s20, 0x100
	s_addc_u32 s21, s21, 0
	s_cmp_gt_u32 s22, 13
	s_barrier
	s_cbranch_scc1 .Lpeel_out_242

.Lpeel_out_242:
	s_add_i32 s0, s66, -8
	s_cmp_lt_u32 s0, 12
	s_mov_b64 s[0:1], -1
	s_cbranch_scc1 .LBB0_266
	s_cmp_gt_i32 s66, 33
	s_cselect_b64 s[64:65], -1, 0
	s_lshl_b32 s0, s66, 8
	s_lshl_b32 s53, s60, 8
	s_add_i32 s1, s0, 0xffffee00
	s_cmp_lt_i32 s66, 26
	v_cndmask_b32_e64 v2, 0, 1, s[80:81]
	s_cselect_b32 s62, s0, s1
	s_mov_b64 s[0:1], -1
	s_and_b64 vcc, exec, s[64:65]
	v_cmp_ne_u32_e64 s[44:45], 1, v2
	s_cbranch_vccz .LBB0_248
	s_and_b64 vcc, exec, s[44:45]
	s_cbranch_vccnz .LBB0_247
	v_add_u32_e32 v132, s53, v185
	v_ashrrev_i32_e32 v133, 31, v132
	v_lshlrev_b64 v[140:141], 7, v[132:133]
	global_load_dwordx4 v[132:135], v[188:189], off offset:16
	global_load_dwordx4 v[136:139], v[188:189], off
	s_mov_b32 s3, 0xbfb8aa3b
	s_mov_b32 s2, 0x800000
	s_mov_b32 s5, 0x3f317217
	s_mov_b32 s6, 0x7f800000
	s_waitcnt vmcnt(0)
	v_add_f32_e32 v147, v126, v134
	v_add_f32_e32 v2, v128, v136
	v_max_f32_e32 v142, 0, v2
	v_mul_f32_e64 v2, |v2|, s3
	v_exp_f32_e32 v2, v2
	v_add_f32_e32 v136, v124, v132
	v_add_f32_e32 v149, v127, v135
	v_add_f32_e32 v2, 1.0, v2
	v_cmp_gt_f32_e32 vcc, s2, v2
	s_nop 1
	v_cndmask_b32_e64 v132, 0, 32, vcc
	v_ldexp_f32 v2, v2, v132
	v_log_f32_e32 v2, v2
	s_nop 0
	v_mul_f32_e32 v132, 0x3f317217, v2
	v_fma_f32 v132, v2, s5, -v132
	v_fmac_f32_e32 v132, 0x3377d1cf, v2
	v_fmac_f32_e32 v132, 0x3f317217, v2
	v_cmp_lt_f32_e64 s[0:1], |v2|, s6
	s_nop 1
	v_cndmask_b32_e64 v2, v2, v132, s[0:1]
	v_cndmask_b32_e32 v132, 0, v228, vcc
	v_sub_f32_e32 v144, v2, v132
	v_mul_f32_e64 v2, |v136|, s3
	v_exp_f32_e32 v2, v2
	v_max_f32_e32 v132, 0, v136
	v_add_f32_e32 v2, 1.0, v2
	v_cmp_gt_f32_e32 vcc, s2, v2
	s_nop 1
	v_cndmask_b32_e64 v136, 0, 32, vcc
	v_ldexp_f32 v2, v2, v136
	v_log_f32_e32 v2, v2
	s_nop 0
	v_mul_f32_e32 v136, 0x3f317217, v2
	v_fma_f32 v136, v2, s5, -v136
	v_fmac_f32_e32 v136, 0x3377d1cf, v2
	v_fmac_f32_e32 v136, 0x3f317217, v2
	v_cmp_lt_f32_e64 s[0:1], |v2|, s6
	s_nop 1
	v_cndmask_b32_e64 v2, v2, v136, s[0:1]
	v_cndmask_b32_e32 v136, 0, v228, vcc
	v_sub_f32_e32 v136, v2, v136
	v_add_f32_e32 v2, v129, v137
	v_max_f32_e32 v143, 0, v2
	v_mul_f32_e64 v2, |v2|, s3
	v_exp_f32_e32 v2, v2
	v_add_f32_e32 v137, v125, v133
	v_add_f32_e32 v2, 1.0, v2
	v_cmp_gt_f32_e32 vcc, s2, v2
	s_nop 1
	v_cndmask_b32_e64 v133, 0, 32, vcc
	v_ldexp_f32 v2, v2, v133
	v_log_f32_e32 v2, v2
	s_nop 0
	v_mul_f32_e32 v133, 0x3f317217, v2
	v_fma_f32 v133, v2, s5, -v133
	v_fmac_f32_e32 v133, 0x3377d1cf, v2
	v_fmac_f32_e32 v133, 0x3f317217, v2
	v_cmp_lt_f32_e64 s[0:1], |v2|, s6
	s_nop 1
	v_cndmask_b32_e64 v2, v2, v133, s[0:1]
	v_cndmask_b32_e32 v133, 0, v228, vcc
	v_sub_f32_e32 v145, v2, v133
	v_mul_f32_e64 v2, |v137|, s3
	v_exp_f32_e32 v2, v2
	v_max_f32_e32 v133, 0, v137
	v_pk_add_f32 v[142:143], v[142:143], v[144:145]
	v_add_f32_e32 v2, 1.0, v2
	v_cmp_gt_f32_e32 vcc, s2, v2
	s_nop 1
	v_cndmask_b32_e64 v137, 0, 32, vcc
	v_ldexp_f32 v2, v2, v137
	v_log_f32_e32 v2, v2
	s_nop 0
	v_mul_f32_e32 v137, 0x3f317217, v2
	v_fma_f32 v137, v2, s5, -v137
	v_fmac_f32_e32 v137, 0x3377d1cf, v2
	v_fmac_f32_e32 v137, 0x3f317217, v2
	v_cmp_lt_f32_e64 s[0:1], |v2|, s6
	s_nop 1
	v_cndmask_b32_e64 v2, v2, v137, s[0:1]
	v_cndmask_b32_e32 v137, 0, v228, vcc
	v_sub_f32_e32 v137, v2, v137
	v_add_f32_e32 v2, v130, v138
	v_max_f32_e32 v138, 0, v2
	v_mul_f32_e64 v2, |v2|, s3
	v_exp_f32_e32 v2, v2
	v_pk_add_f32 v[132:133], v[132:133], v[136:137]
	v_lshl_add_u64 v[136:137], v[190:191], 0, v[140:141]
	v_add_f32_e32 v2, 1.0, v2
	v_cmp_gt_f32_e32 vcc, s2, v2
	s_nop 1
	v_cndmask_b32_e64 v134, 0, 32, vcc
	v_ldexp_f32 v2, v2, v134
	v_log_f32_e32 v2, v2
	s_nop 0
	v_mul_f32_e32 v134, 0x3f317217, v2
	v_fma_f32 v134, v2, s5, -v134
	v_fmac_f32_e32 v134, 0x3377d1cf, v2
	v_fmac_f32_e32 v134, 0x3f317217, v2
	v_cmp_lt_f32_e64 s[0:1], |v2|, s6
	s_nop 1
	v_cndmask_b32_e64 v2, v2, v134, s[0:1]
	v_cndmask_b32_e32 v134, 0, v228, vcc
	v_sub_f32_e32 v146, v2, v134
	v_mul_f32_e64 v2, |v147|, s3
	v_exp_f32_e32 v2, v2
	v_max_f32_e32 v134, 0, v147
	v_add_f32_e32 v2, 1.0, v2
	v_cmp_gt_f32_e32 vcc, s2, v2
	s_nop 1
	v_cndmask_b32_e64 v147, 0, 32, vcc
	v_ldexp_f32 v2, v2, v147
	v_log_f32_e32 v2, v2
	s_nop 0
	v_mul_f32_e32 v147, 0x3f317217, v2
	v_fma_f32 v147, v2, s5, -v147
	v_fmac_f32_e32 v147, 0x3377d1cf, v2
	v_fmac_f32_e32 v147, 0x3f317217, v2
	v_cmp_lt_f32_e64 s[0:1], |v2|, s6
	s_nop 1
	v_cndmask_b32_e64 v2, v2, v147, s[0:1]
	v_cndmask_b32_e32 v147, 0, v228, vcc
	v_sub_f32_e32 v148, v2, v147
	v_add_f32_e32 v2, v131, v139
	v_max_f32_e32 v139, 0, v2
	v_mul_f32_e64 v2, |v2|, s3
	v_exp_f32_e32 v2, v2
	s_nop 0
	v_add_f32_e32 v2, 1.0, v2
	v_cmp_gt_f32_e32 vcc, s2, v2
	s_nop 1
	v_cndmask_b32_e64 v135, 0, 32, vcc
	v_ldexp_f32 v2, v2, v135
	v_log_f32_e32 v2, v2
	s_nop 0
	v_mul_f32_e32 v135, 0x3f317217, v2
	v_fma_f32 v135, v2, s5, -v135
	v_fmac_f32_e32 v135, 0x3377d1cf, v2
	v_fmac_f32_e32 v135, 0x3f317217, v2
	v_cmp_lt_f32_e64 s[0:1], |v2|, s6
	s_nop 1
	v_cndmask_b32_e64 v2, v2, v135, s[0:1]
	v_cndmask_b32_e32 v135, 0, v228, vcc
	v_sub_f32_e32 v147, v2, v135
	v_mul_f32_e64 v2, |v149|, s3
	v_exp_f32_e32 v2, v2
	v_pk_add_f32 v[144:145], v[138:139], v[146:147]
	v_max_f32_e32 v135, 0, v149
	v_add_f32_e32 v2, 1.0, v2
	v_cmp_gt_f32_e32 vcc, s2, v2
	s_nop 1
	v_cndmask_b32_e64 v138, 0, 32, vcc
	v_ldexp_f32 v2, v2, v138
	v_log_f32_e32 v2, v2
	s_nop 0
	v_mul_f32_e32 v138, 0x3f317217, v2
	v_fma_f32 v138, v2, s5, -v138
	v_fmac_f32_e32 v138, 0x3377d1cf, v2
	v_fmac_f32_e32 v138, 0x3f317217, v2
	v_cmp_lt_f32_e64 s[0:1], |v2|, s6
	s_nop 1
	v_cndmask_b32_e64 v2, v2, v138, s[0:1]
	v_cndmask_b32_e32 v138, 0, v228, vcc
	v_sub_f32_e32 v149, v2, v138
	v_pk_add_f32 v[134:135], v[134:135], v[148:149]
	global_store_dwordx4 v[136:137], v[142:145], off
	global_store_dwordx4 v[136:137], v[132:135], off offset:16

.LBB0_426:
	s_add_u32 s0, s0, 0x40080
	s_addc_u32 s1, s1, 0
	s_add_u32 s20, s44, 0x100
	s_addc_u32 s21, s45, 0
	s_mov_b32 s22, -2
	v_add_u32_e32 v216, 0x10000, v187
	s_add_u32 s23, s0, 0xfffc0080
	s_addc_u32 s24, s1, -1
	s_add_i32 s25, 0, 0x10000
	ds_read_b128 v[132:135], v216
	ds_read_b128 v[136:139], v216 offset:1024
	ds_read_b128 v[140:143], v216 offset:2048
	ds_read_b128 v[144:147], v216 offset:3072
	s_cmp_eq_u32 s22, 12
	s_cselect_b32 s47, s57, s24
	s_cselect_b32 s46, s56, s23
	s_cselect_b32 s45, s59, s21
	s_cselect_b32 s44, s58, s20
	s_add_i32 m0, s74, 0xc000
	ds_read_b128 v[148:151], v240
	ds_read_b128 v[152:155], v240 offset:1024
	ds_read_b128 v[156:159], v240 offset:2048
	ds_read_b128 v[160:163], v240 offset:3072
	ds_read_b128 v[164:167], v240 offset:4096
	ds_read_b128 v[168:171], v240 offset:5120
	ds_read_b128 v[172:175], v240 offset:6144
	global_load_lds_dwordx4 v194, s[0:1]
	s_add_i32 m0, s74, 0xe000
	ds_read_b128 v[204:207], v240 offset:7168
	global_load_lds_dwordx4 v202, s[0:1]
	s_waitcnt lgkmcnt(8)
	s_barrier
	s_waitcnt lgkmcnt(0)
	v_mfma_f32_16x16x32_bf16 v[128:131], v[132:135], v[148:151], 0
	v_mfma_f32_16x16x32_bf16 v[124:127], v[140:143], v[148:151], 0
	v_mfma_f32_16x16x32_bf16 v[120:123], v[132:135], v[156:159], 0
	v_mfma_f32_16x16x32_bf16 v[116:119], v[140:143], v[156:159], 0
	v_mfma_f32_16x16x32_bf16 v[112:115], v[132:135], v[164:167], 0
	v_mfma_f32_16x16x32_bf16 v[108:111], v[140:143], v[164:167], 0
	v_mfma_f32_16x16x32_bf16 v[104:107], v[132:135], v[172:175], 0
	v_mfma_f32_16x16x32_bf16 v[100:103], v[140:143], v[172:175], 0
	v_mfma_f32_16x16x32_bf16 v[128:131], v[136:139], v[152:155], v[128:131]
	v_mfma_f32_16x16x32_bf16 v[124:127], v[144:147], v[152:155], v[124:127]
	v_mfma_f32_16x16x32_bf16 v[120:123], v[136:139], v[160:163], v[120:123]
	v_mfma_f32_16x16x32_bf16 v[116:119], v[144:147], v[160:163], v[116:119]
	v_mfma_f32_16x16x32_bf16 v[112:115], v[136:139], v[168:171], v[112:115]
	v_mfma_f32_16x16x32_bf16 v[108:111], v[144:147], v[168:171], v[108:111]
	v_mfma_f32_16x16x32_bf16 v[104:107], v[136:139], v[204:207], v[104:107]
	v_mfma_f32_16x16x32_bf16 v[100:103], v[144:147], v[204:207], v[100:103]
	s_barrier
	s_add_i32 s23, 0, 0x14000
	s_add_i32 s24, s25, s67
	s_mov_b32 m0, s24
	ds_read_b128 v[208:211], v216 offset:16384
	ds_read_b128 v[212:215], v216 offset:17408
	ds_read_b128 v[242:245], v216 offset:18432
	global_load_lds_dwordx4 v176, s[44:45]
	s_add_i32 m0, s24, 0x2000
	ds_read_b128 v[246:249], v216 offset:19456
	global_load_lds_dwordx4 v180, s[44:45]
	s_barrier
	s_waitcnt lgkmcnt(0)
	v_mfma_f32_16x16x32_bf16 v[64:67], v[208:211], v[148:151], 0
	v_mfma_f32_16x16x32_bf16 v[60:63], v[242:245], v[148:151], 0
	v_mfma_f32_16x16x32_bf16 v[56:59], v[208:211], v[156:159], 0
	v_mfma_f32_16x16x32_bf16 v[52:55], v[242:245], v[156:159], 0
	v_mfma_f32_16x16x32_bf16 v[48:51], v[208:211], v[164:167], 0
	v_mfma_f32_16x16x32_bf16 v[44:47], v[242:245], v[164:167], 0
	v_mfma_f32_16x16x32_bf16 v[40:43], v[208:211], v[172:175], 0
	v_mfma_f32_16x16x32_bf16 v[36:39], v[242:245], v[172:175], 0
	v_mfma_f32_16x16x32_bf16 v[64:67], v[212:215], v[152:155], v[64:67]
	v_mfma_f32_16x16x32_bf16 v[60:63], v[246:249], v[152:155], v[60:63]
	v_mfma_f32_16x16x32_bf16 v[56:59], v[212:215], v[160:163], v[56:59]
	v_mfma_f32_16x16x32_bf16 v[52:55], v[246:249], v[160:163], v[52:55]
	v_mfma_f32_16x16x32_bf16 v[48:51], v[212:215], v[168:171], v[48:51]
	v_mfma_f32_16x16x32_bf16 v[44:47], v[246:249], v[168:171], v[44:47]
	v_mfma_f32_16x16x32_bf16 v[40:43], v[212:215], v[204:207], v[40:43]
	v_mfma_f32_16x16x32_bf16 v[36:39], v[246:249], v[204:207], v[36:39]
	s_mov_b32 m0, s74
	s_barrier
	ds_read_b128 v[148:151], v240 offset:16384
	ds_read_b128 v[152:155], v240 offset:17408
	ds_read_b128 v[156:159], v240 offset:18432
	ds_read_b128 v[160:163], v240 offset:19456
	ds_read_b128 v[164:167], v240 offset:20480
	ds_read_b128 v[168:171], v240 offset:21504
	ds_read_b128 v[172:175], v240 offset:22528
	global_load_lds_dwordx4 v0, s[46:47]
	s_mov_b32 m0, s75
	ds_read_b128 v[204:207], v240 offset:23552
	global_load_lds_dwordx4 v178, s[46:47]
	s_barrier
	s_waitcnt lgkmcnt(0)
	v_mfma_f32_16x16x32_bf16 v[96:99], v[132:135], v[148:151], 0
	v_mfma_f32_16x16x32_bf16 v[92:95], v[140:143], v[148:151], 0
	v_mfma_f32_16x16x32_bf16 v[88:91], v[132:135], v[156:159], 0
	v_mfma_f32_16x16x32_bf16 v[84:87], v[140:143], v[156:159], 0
	v_mfma_f32_16x16x32_bf16 v[80:83], v[132:135], v[164:167], 0
	v_mfma_f32_16x16x32_bf16 v[76:79], v[140:143], v[164:167], 0
	v_mfma_f32_16x16x32_bf16 v[72:75], v[132:135], v[172:175], 0
	v_mfma_f32_16x16x32_bf16 v[68:71], v[140:143], v[172:175], 0
	v_mfma_f32_16x16x32_bf16 v[96:99], v[136:139], v[152:155], v[96:99]
	v_mfma_f32_16x16x32_bf16 v[92:95], v[144:147], v[152:155], v[92:95]
	v_mfma_f32_16x16x32_bf16 v[88:91], v[136:139], v[160:163], v[88:91]
	v_mfma_f32_16x16x32_bf16 v[84:87], v[144:147], v[160:163], v[84:87]
	v_mfma_f32_16x16x32_bf16 v[80:83], v[136:139], v[168:171], v[80:83]
	v_mfma_f32_16x16x32_bf16 v[76:79], v[144:147], v[168:171], v[76:79]
	v_mfma_f32_16x16x32_bf16 v[72:75], v[136:139], v[204:207], v[72:75]
	v_mfma_f32_16x16x32_bf16 v[68:71], v[144:147], v[204:207], v[68:71]
	s_barrier
	s_add_i32 s23, s23, s67
	s_mov_b32 m0, s23
	s_add_u32 s24, s44, 0x40000
	s_addc_u32 s25, s45, 0
	global_load_lds_dwordx4 v176, s[24:25]
	s_add_i32 m0, s23, 0x2000
	s_waitcnt vmcnt(5)
	global_load_lds_dwordx4 v180, s[24:25]
	s_barrier
	v_mfma_f32_16x16x32_bf16 v[32:35], v[208:211], v[148:151], 0
	v_mfma_f32_16x16x32_bf16 v[28:31], v[242:245], v[148:151], 0
	v_mfma_f32_16x16x32_bf16 v[24:27], v[208:211], v[156:159], 0
	v_mfma_f32_16x16x32_bf16 v[20:23], v[242:245], v[156:159], 0
	v_mfma_f32_16x16x32_bf16 v[16:19], v[208:211], v[164:167], 0
	v_mfma_f32_16x16x32_bf16 v[12:15], v[242:245], v[164:167], 0
	v_mfma_f32_16x16x32_bf16 v[8:11], v[208:211], v[172:175], 0
	v_mfma_f32_16x16x32_bf16 v[4:7], v[242:245], v[172:175], 0
	v_mfma_f32_16x16x32_bf16 v[32:35], v[212:215], v[152:155], v[32:35]
	v_mfma_f32_16x16x32_bf16 v[28:31], v[246:249], v[152:155], v[28:31]
	v_mfma_f32_16x16x32_bf16 v[24:27], v[212:215], v[160:163], v[24:27]
	v_mfma_f32_16x16x32_bf16 v[20:23], v[246:249], v[160:163], v[20:23]
	v_mfma_f32_16x16x32_bf16 v[16:19], v[212:215], v[168:171], v[16:19]
	v_mfma_f32_16x16x32_bf16 v[12:15], v[246:249], v[168:171], v[12:15]
	v_mfma_f32_16x16x32_bf16 v[8:11], v[212:215], v[204:207], v[8:11]
	v_mfma_f32_16x16x32_bf16 v[4:7], v[246:249], v[204:207], v[4:7]
	s_add_i32 s23, 0, 0x18000
	s_barrier
	ds_read_b128 v[132:135], v216 offset:32768
	ds_read_b128 v[136:139], v216 offset:33792
	ds_read_b128 v[140:143], v216 offset:34816
	ds_read_b128 v[144:147], v216 offset:35840
	s_add_u32 s24, s46, 0x40000
	s_addc_u32 s25, s47, 0
	s_mov_b32 m0, s82
	ds_read_b128 v[148:151], v240 offset:32768
	ds_read_b128 v[152:155], v240 offset:33792
	ds_read_b128 v[156:159], v240 offset:34816
	ds_read_b128 v[160:163], v240 offset:35840
	ds_read_b128 v[164:167], v240 offset:36864
	ds_read_b128 v[168:171], v240 offset:37888
	ds_read_b128 v[172:175], v240 offset:38912
	global_load_lds_dwordx4 v0, s[24:25]
	s_mov_b32 m0, s83
	ds_read_b128 v[204:207], v240 offset:39936
	global_load_lds_dwordx4 v178, s[24:25]
	s_waitcnt lgkmcnt(8)
	s_barrier
	s_waitcnt lgkmcnt(0)
	v_mfma_f32_16x16x32_bf16 v[128:131], v[132:135], v[148:151], v[128:131]
	v_mfma_f32_16x16x32_bf16 v[124:127], v[140:143], v[148:151], v[124:127]
	v_mfma_f32_16x16x32_bf16 v[120:123], v[132:135], v[156:159], v[120:123]
	v_mfma_f32_16x16x32_bf16 v[116:119], v[140:143], v[156:159], v[116:119]
	v_mfma_f32_16x16x32_bf16 v[112:115], v[132:135], v[164:167], v[112:115]
	v_mfma_f32_16x16x32_bf16 v[108:111], v[140:143], v[164:167], v[108:111]
	v_mfma_f32_16x16x32_bf16 v[104:107], v[132:135], v[172:175], v[104:107]
	v_mfma_f32_16x16x32_bf16 v[100:103], v[140:143], v[172:175], v[100:103]
	v_mfma_f32_16x16x32_bf16 v[128:131], v[136:139], v[152:155], v[128:131]
	v_mfma_f32_16x16x32_bf16 v[124:127], v[144:147], v[152:155], v[124:127]
	v_mfma_f32_16x16x32_bf16 v[120:123], v[136:139], v[160:163], v[120:123]
	v_mfma_f32_16x16x32_bf16 v[116:119], v[144:147], v[160:163], v[116:119]
	v_mfma_f32_16x16x32_bf16 v[112:115], v[136:139], v[168:171], v[112:115]
	v_mfma_f32_16x16x32_bf16 v[108:111], v[144:147], v[168:171], v[108:111]
	v_mfma_f32_16x16x32_bf16 v[104:107], v[136:139], v[204:207], v[104:107]
	v_mfma_f32_16x16x32_bf16 v[100:103], v[144:147], v[204:207], v[100:103]
	s_barrier
	s_add_i32 s26, 0, 0x1c000
	s_add_i32 s23, s23, s67
	s_mov_b32 m0, s23
	ds_read_b128 v[208:211], v216 offset:49152
	ds_read_b128 v[212:215], v216 offset:50176
	ds_read_b128 v[242:245], v216 offset:51200
	s_add_u32 s98, s44, 0x80
	s_addc_u32 s99, s45, 0
	global_load_lds_dwordx4 v176, s[98:99]
	s_add_i32 m0, s23, 0x2000
	ds_read_b128 v[246:249], v216 offset:52224
	global_load_lds_dwordx4 v180, s[98:99]
	s_barrier
	s_waitcnt lgkmcnt(0)
	v_mfma_f32_16x16x32_bf16 v[64:67], v[208:211], v[148:151], v[64:67]
	v_mfma_f32_16x16x32_bf16 v[60:63], v[242:245], v[148:151], v[60:63]
	v_mfma_f32_16x16x32_bf16 v[56:59], v[208:211], v[156:159], v[56:59]
	v_mfma_f32_16x16x32_bf16 v[52:55], v[242:245], v[156:159], v[52:55]
	v_mfma_f32_16x16x32_bf16 v[48:51], v[208:211], v[164:167], v[48:51]
	v_mfma_f32_16x16x32_bf16 v[44:47], v[242:245], v[164:167], v[44:47]
	v_mfma_f32_16x16x32_bf16 v[40:43], v[208:211], v[172:175], v[40:43]
	v_mfma_f32_16x16x32_bf16 v[36:39], v[242:245], v[172:175], v[36:39]
	v_mfma_f32_16x16x32_bf16 v[64:67], v[212:215], v[152:155], v[64:67]
	v_mfma_f32_16x16x32_bf16 v[60:63], v[246:249], v[152:155], v[60:63]
	v_mfma_f32_16x16x32_bf16 v[56:59], v[212:215], v[160:163], v[56:59]
	v_mfma_f32_16x16x32_bf16 v[52:55], v[246:249], v[160:163], v[52:55]
	v_mfma_f32_16x16x32_bf16 v[48:51], v[212:215], v[168:171], v[48:51]
	v_mfma_f32_16x16x32_bf16 v[44:47], v[246:249], v[168:171], v[44:47]
	v_mfma_f32_16x16x32_bf16 v[40:43], v[212:215], v[204:207], v[40:43]
	v_mfma_f32_16x16x32_bf16 v[36:39], v[246:249], v[204:207], v[36:39]
	s_mov_b32 m0, s48
	s_barrier
	ds_read_b128 v[148:151], v240 offset:49152
	ds_read_b128 v[152:155], v240 offset:50176
	ds_read_b128 v[156:159], v240 offset:51200
	ds_read_b128 v[160:163], v240 offset:52224
	ds_read_b128 v[164:167], v240 offset:53248
	ds_read_b128 v[168:171], v240 offset:54272
	ds_read_b128 v[172:175], v240 offset:55296
	s_add_u32 s98, s46, 0x80
	s_addc_u32 s99, s47, 0
	global_load_lds_dwordx4 v0, s[98:99]
	s_mov_b32 m0, s50
	ds_read_b128 v[204:207], v240 offset:56320
	global_load_lds_dwordx4 v178, s[98:99]
	s_barrier
	s_waitcnt lgkmcnt(0)
	v_mfma_f32_16x16x32_bf16 v[96:99], v[132:135], v[148:151], v[96:99]
	v_mfma_f32_16x16x32_bf16 v[92:95], v[140:143], v[148:151], v[92:95]
	v_mfma_f32_16x16x32_bf16 v[88:91], v[132:135], v[156:159], v[88:91]
	v_mfma_f32_16x16x32_bf16 v[84:87], v[140:143], v[156:159], v[84:87]
	v_mfma_f32_16x16x32_bf16 v[80:83], v[132:135], v[164:167], v[80:83]
	v_mfma_f32_16x16x32_bf16 v[76:79], v[140:143], v[164:167], v[76:79]
	v_mfma_f32_16x16x32_bf16 v[72:75], v[132:135], v[172:175], v[72:75]
	v_mfma_f32_16x16x32_bf16 v[68:71], v[140:143], v[172:175], v[68:71]
	v_mfma_f32_16x16x32_bf16 v[96:99], v[136:139], v[152:155], v[96:99]
	v_mfma_f32_16x16x32_bf16 v[92:95], v[144:147], v[152:155], v[92:95]
	v_mfma_f32_16x16x32_bf16 v[88:91], v[136:139], v[160:163], v[88:91]
	v_mfma_f32_16x16x32_bf16 v[84:87], v[144:147], v[160:163], v[84:87]
	v_mfma_f32_16x16x32_bf16 v[80:83], v[136:139], v[168:171], v[80:83]
	v_mfma_f32_16x16x32_bf16 v[76:79], v[144:147], v[168:171], v[76:79]
	v_mfma_f32_16x16x32_bf16 v[72:75], v[136:139], v[204:207], v[72:75]
	v_mfma_f32_16x16x32_bf16 v[68:71], v[144:147], v[204:207], v[68:71]
	s_barrier
	s_add_i32 s23, s26, s67
	s_mov_b32 m0, s23
	s_add_u32 s24, s44, 0x40080
	s_addc_u32 s25, s45, 0
	global_load_lds_dwordx4 v176, s[24:25]
	s_add_i32 m0, s23, 0x2000
	s_waitcnt vmcnt(5)
	global_load_lds_dwordx4 v180, s[24:25]
	s_barrier
	v_mfma_f32_16x16x32_bf16 v[32:35], v[208:211], v[148:151], v[32:35]
	v_mfma_f32_16x16x32_bf16 v[28:31], v[242:245], v[148:151], v[28:31]
	v_mfma_f32_16x16x32_bf16 v[24:27], v[208:211], v[156:159], v[24:27]
	v_mfma_f32_16x16x32_bf16 v[20:23], v[242:245], v[156:159], v[20:23]
	v_mfma_f32_16x16x32_bf16 v[16:19], v[208:211], v[164:167], v[16:19]
	v_mfma_f32_16x16x32_bf16 v[12:15], v[242:245], v[164:167], v[12:15]
	v_mfma_f32_16x16x32_bf16 v[8:11], v[208:211], v[172:175], v[8:11]
	v_mfma_f32_16x16x32_bf16 v[4:7], v[242:245], v[172:175], v[4:7]
	v_mfma_f32_16x16x32_bf16 v[32:35], v[212:215], v[152:155], v[32:35]
	v_mfma_f32_16x16x32_bf16 v[28:31], v[246:249], v[152:155], v[28:31]
	v_mfma_f32_16x16x32_bf16 v[24:27], v[212:215], v[160:163], v[24:27]
	v_mfma_f32_16x16x32_bf16 v[20:23], v[246:249], v[160:163], v[20:23]
	v_mfma_f32_16x16x32_bf16 v[16:19], v[212:215], v[168:171], v[16:19]
	v_mfma_f32_16x16x32_bf16 v[12:15], v[246:249], v[168:171], v[12:15]
	v_mfma_f32_16x16x32_bf16 v[8:11], v[212:215], v[204:207], v[8:11]
	v_mfma_f32_16x16x32_bf16 v[4:7], v[246:249], v[204:207], v[4:7]
	s_add_i32 s22, s22, 2
	s_add_u32 s0, s0, 0x100
	s_addc_u32 s1, s1, 0
	s_add_u32 s20, s20, 0x100
	s_addc_u32 s21, s21, 0
	s_cmp_gt_u32 s22, 13
	s_barrier
	s_cbranch_scc1 .Lpeel_out_427

.Lpeel_out_427:
	s_add_i32 s0, s61, -8
	s_cmp_lt_u32 s0, 12
	s_mov_b64 s[0:1], -1
	s_cbranch_scc1 .LBB0_451
	s_cmp_gt_i32 s61, 33
	s_cselect_b64 s[64:65], -1, 0
	s_lshl_b32 s0, s61, 8
	s_lshl_b32 s53, s60, 8
	s_add_i32 s1, s0, 0xffffee00
	s_cmp_lt_i32 s61, 26
	v_cndmask_b32_e64 v2, 0, 1, s[36:37]
	s_cselect_b32 s62, s0, s1
	s_mov_b64 s[0:1], -1
	s_and_b64 vcc, exec, s[64:65]
	v_cmp_ne_u32_e64 s[44:45], 1, v2
	s_cbranch_vccz .LBB0_433
	s_and_b64 vcc, exec, s[44:45]
	s_cbranch_vccnz .LBB0_432
	v_add_u32_e32 v132, s53, v185
	v_ashrrev_i32_e32 v133, 31, v132
	v_lshlrev_b64 v[140:141], 7, v[132:133]
	global_load_dwordx4 v[204:207], v[188:189], off offset:16
	global_load_dwordx4 v[208:211], v[188:189], off
	s_mov_b32 s3, 0xbfb8aa3b
	s_mov_b32 s2, 0x800000
	s_mov_b32 s4, 0x3f317217
	s_mov_b32 s5, 0x7f800000
	s_waitcnt vmcnt(0)
	v_mov_b32_e32 v132, v204
	v_mov_b32_e32 v133, v205
	v_mov_b32_e32 v134, v206
	v_mov_b32_e32 v135, v207
	v_mov_b32_e32 v136, v208
	v_mov_b32_e32 v137, v209
	v_mov_b32_e32 v138, v210
	v_mov_b32_e32 v139, v211
	v_add_f32_e32 v147, v126, v134
	v_add_f32_e32 v2, v128, v136
	v_max_f32_e32 v142, 0, v2
	v_mul_f32_e64 v2, |v2|, s3
	v_exp_f32_e32 v2, v2
	v_add_f32_e32 v136, v124, v132
	v_add_f32_e32 v149, v127, v135
	v_add_f32_e32 v2, 1.0, v2
	v_cmp_gt_f32_e32 vcc, s2, v2
	s_nop 1
	v_cndmask_b32_e64 v132, 0, 32, vcc
	v_ldexp_f32 v2, v2, v132
	v_log_f32_e32 v2, v2
	s_nop 0
	v_mul_f32_e32 v132, 0x3f317217, v2
	v_fma_f32 v132, v2, s4, -v132
	v_fmac_f32_e32 v132, 0x3377d1cf, v2
	v_fmac_f32_e32 v132, 0x3f317217, v2
	v_cmp_lt_f32_e64 s[0:1], |v2|, s5
	s_nop 1
	v_cndmask_b32_e64 v2, v2, v132, s[0:1]
	v_cndmask_b32_e32 v132, 0, v228, vcc
	v_sub_f32_e32 v144, v2, v132
	v_mul_f32_e64 v2, |v136|, s3
	v_exp_f32_e32 v2, v2
	v_max_f32_e32 v132, 0, v136
	v_add_f32_e32 v2, 1.0, v2
	v_cmp_gt_f32_e32 vcc, s2, v2
	s_nop 1
	v_cndmask_b32_e64 v136, 0, 32, vcc
	v_ldexp_f32 v2, v2, v136
	v_log_f32_e32 v2, v2
	s_nop 0
	v_mul_f32_e32 v136, 0x3f317217, v2
	v_fma_f32 v136, v2, s4, -v136
	v_fmac_f32_e32 v136, 0x3377d1cf, v2
	v_fmac_f32_e32 v136, 0x3f317217, v2
	v_cmp_lt_f32_e64 s[0:1], |v2|, s5
	s_nop 1
	v_cndmask_b32_e64 v2, v2, v136, s[0:1]
	v_cndmask_b32_e32 v136, 0, v228, vcc
	v_sub_f32_e32 v136, v2, v136
	v_add_f32_e32 v2, v129, v137
	v_max_f32_e32 v143, 0, v2
	v_mul_f32_e64 v2, |v2|, s3
	v_exp_f32_e32 v2, v2
	v_add_f32_e32 v137, v125, v133
	v_add_f32_e32 v2, 1.0, v2
	v_cmp_gt_f32_e32 vcc, s2, v2
	s_nop 1
	v_cndmask_b32_e64 v133, 0, 32, vcc
	v_ldexp_f32 v2, v2, v133
	v_log_f32_e32 v2, v2
	s_nop 0
	v_mul_f32_e32 v133, 0x3f317217, v2
	v_fma_f32 v133, v2, s4, -v133
	v_fmac_f32_e32 v133, 0x3377d1cf, v2
	v_fmac_f32_e32 v133, 0x3f317217, v2
	v_cmp_lt_f32_e64 s[0:1], |v2|, s5
	s_nop 1
	v_cndmask_b32_e64 v2, v2, v133, s[0:1]
	v_cndmask_b32_e32 v133, 0, v228, vcc
	v_sub_f32_e32 v145, v2, v133
	v_mul_f32_e64 v2, |v137|, s3
	v_exp_f32_e32 v2, v2
	v_max_f32_e32 v133, 0, v137
	v_pk_add_f32 v[142:143], v[142:143], v[144:145]
	v_add_f32_e32 v2, 1.0, v2
	v_cmp_gt_f32_e32 vcc, s2, v2
	s_nop 1
	v_cndmask_b32_e64 v137, 0, 32, vcc
	v_ldexp_f32 v2, v2, v137
	v_log_f32_e32 v2, v2
	s_nop 0
	v_mul_f32_e32 v137, 0x3f317217, v2
	v_fma_f32 v137, v2, s4, -v137
	v_fmac_f32_e32 v137, 0x3377d1cf, v2
	v_fmac_f32_e32 v137, 0x3f317217, v2
	v_cmp_lt_f32_e64 s[0:1], |v2|, s5
	s_nop 1
	v_cndmask_b32_e64 v2, v2, v137, s[0:1]
	v_cndmask_b32_e32 v137, 0, v228, vcc
	v_sub_f32_e32 v137, v2, v137
	v_add_f32_e32 v2, v130, v138
	v_max_f32_e32 v138, 0, v2
	v_mul_f32_e64 v2, |v2|, s3
	v_exp_f32_e32 v2, v2
	v_pk_add_f32 v[132:133], v[132:133], v[136:137]
	v_lshl_add_u64 v[136:137], v[190:191], 0, v[140:141]
	v_add_f32_e32 v2, 1.0, v2
	v_cmp_gt_f32_e32 vcc, s2, v2
	s_nop 1
	v_cndmask_b32_e64 v134, 0, 32, vcc
	v_ldexp_f32 v2, v2, v134
	v_log_f32_e32 v2, v2
	s_nop 0
	v_mul_f32_e32 v134, 0x3f317217, v2
	v_fma_f32 v134, v2, s4, -v134
	v_fmac_f32_e32 v134, 0x3377d1cf, v2
	v_fmac_f32_e32 v134, 0x3f317217, v2
	v_cmp_lt_f32_e64 s[0:1], |v2|, s5
	s_nop 1
	v_cndmask_b32_e64 v2, v2, v134, s[0:1]
	v_cndmask_b32_e32 v134, 0, v228, vcc
	v_sub_f32_e32 v146, v2, v134
	v_mul_f32_e64 v2, |v147|, s3
	v_exp_f32_e32 v2, v2
	v_max_f32_e32 v134, 0, v147
	v_add_f32_e32 v2, 1.0, v2
	v_cmp_gt_f32_e32 vcc, s2, v2
	s_nop 1
	v_cndmask_b32_e64 v147, 0, 32, vcc
	v_ldexp_f32 v2, v2, v147
	v_log_f32_e32 v2, v2
	s_nop 0
	v_mul_f32_e32 v147, 0x3f317217, v2
	v_fma_f32 v147, v2, s4, -v147
	v_fmac_f32_e32 v147, 0x3377d1cf, v2
	v_fmac_f32_e32 v147, 0x3f317217, v2
	v_cmp_lt_f32_e64 s[0:1], |v2|, s5
	s_nop 1
	v_cndmask_b32_e64 v2, v2, v147, s[0:1]
	v_cndmask_b32_e32 v147, 0, v228, vcc
	v_sub_f32_e32 v148, v2, v147
	v_add_f32_e32 v2, v131, v139
	v_max_f32_e32 v139, 0, v2
	v_mul_f32_e64 v2, |v2|, s3
	v_exp_f32_e32 v2, v2
	s_nop 0
	v_add_f32_e32 v2, 1.0, v2
	v_cmp_gt_f32_e32 vcc, s2, v2
	s_nop 1
	v_cndmask_b32_e64 v135, 0, 32, vcc
	v_ldexp_f32 v2, v2, v135
	v_log_f32_e32 v2, v2
	s_nop 0
	v_mul_f32_e32 v135, 0x3f317217, v2
	v_fma_f32 v135, v2, s4, -v135
	v_fmac_f32_e32 v135, 0x3377d1cf, v2
	v_fmac_f32_e32 v135, 0x3f317217, v2
	v_cmp_lt_f32_e64 s[0:1], |v2|, s5
	s_nop 1
	v_cndmask_b32_e64 v2, v2, v135, s[0:1]
	v_cndmask_b32_e32 v135, 0, v228, vcc
	v_sub_f32_e32 v147, v2, v135
	v_mul_f32_e64 v2, |v149|, s3
	v_exp_f32_e32 v2, v2
	v_pk_add_f32 v[144:145], v[138:139], v[146:147]
	v_max_f32_e32 v135, 0, v149
	v_add_f32_e32 v2, 1.0, v2
	v_cmp_gt_f32_e32 vcc, s2, v2
	s_nop 1
	v_cndmask_b32_e64 v138, 0, 32, vcc
	v_ldexp_f32 v2, v2, v138
	v_log_f32_e32 v2, v2
	s_nop 0
	v_mul_f32_e32 v138, 0x3f317217, v2
	v_fma_f32 v138, v2, s4, -v138
	v_fmac_f32_e32 v138, 0x3377d1cf, v2
	v_fmac_f32_e32 v138, 0x3f317217, v2
	v_cmp_lt_f32_e64 s[0:1], |v2|, s5
	s_nop 1
	v_cndmask_b32_e64 v2, v2, v138, s[0:1]
	v_cndmask_b32_e32 v138, 0, v228, vcc
	v_sub_f32_e32 v149, v2, v138
	v_pk_add_f32 v[134:135], v[134:135], v[148:149]
	global_store_dwordx4 v[136:137], v[142:145], off
	global_store_dwordx4 v[136:137], v[132:135], off offset:16
